# GQA units split into two KV halves (768 half-units, pairwise f32 partial combine via dead H region), balances the mixer phase
# baseline (speedup 1.0000x reference)
; __device__ __forceinline__ int opaque_tid() { int t; asm volatile("v_mov_b32 %0, %1" : "=v"(t) : "v"((int)threadIdx.x)); return t; }
; __global__ void __launch_bounds__(NTHREADS, 2) mega_fwd(Params P) {
;     ...
;             for (;;) {
;                 if (opaque_tid() == 0) qslot[0] = (int)atomicAdd(ctl + 64 * (l + 1), 1u);
;                 __syncthreads();
;                 const int idx = __builtin_amdgcn_readfirstlane(qslot[0]);
;                 __syncthreads();
;                 if (idx >= ntot) break;
;                 if (idx < n_gqa) {
;                     const int qb = idx / 12, r12 = idx % 12, b = r12 / 6, h = r12 % 6; const size_t rb = (size_t)b * RPB;
;                     ap::unit<8, 0>(qkv + (rb + 256 * qb) * DIN + C_QC + 64 * h, qkv + rb * DIN + C_KC + 64 * (h / 3), qkv + rb * DIN + C_VC + 64 * (h / 3),
;                                    omix + (rb + 256 * qb) * DM + 640 + 64 * h, ssb + (rb + 256 * qb) * 4 + 2, 132, (char*)lds, 0, 0, tcos[4096 + l]);
;                     publish_cnt(cw + (b * 33 + qb) * 16);
;                 } else if (idx < n_gqa + n_na) {
;                     const int i2 = idx - n_gqa; const int rblk = i2 / 12, r12 = i2 % 12, b = r12 / 6, h = r12 % 6; const size_t rb = (size_t)b * RPB;
;                     { float* bl = (float*)((char*)lds + ap::LDS_NABIAS); const float* src = P.rpb + ((size_t)l * 6 + h) * 465; for (int i = opaque_tid(); i < 465; i += NTHREADS) bl[i] = src[i] * LOG2E; }
;                     __syncthreads();
;                     const int r0 = 4 * rblk, klo = min(max(r0 - 4, 0), 120), khi = min(max(r0 - 1, 0), 120) + 7; const int nlt = (khi - klo + 2) & ~1;
;                     ap::unit<8, 1>(qkv + (rb + 256 * rblk) * DIN + C_QA + 64 * h, qkv + rb * DIN + C_KA + 64 * h, qkv + rb * DIN + C_VA + 64 * h,
;                                    omix + (rb + 256 * rblk) * DM + 64 * h, ssb + (rb + 256 * rblk) * 4 + 0, 4 + nlt, (char*)lds, klo, r0);
;                     publish_cnt(cw + (b * 33 + rblk) * 16);
;                 } else if (idx < n_gqa + n_na + n_sg) {
.LBB0_443:
	s_or_b64 exec, exec, s[0:1]
	v_readlane_b32 s0, v254, 42
	s_waitcnt lgkmcnt(0)
	s_barrier
	v_mov_b32_e32 v0, s0
	ds_read_b32 v0, v0
	s_mov_b64 s[0:1], -1
	s_waitcnt lgkmcnt(0)
	s_barrier
	v_readfirstlane_b32 s48, v0
	s_nop 0
	s_mov_b32 s101, 0
	s_cmpk_lt_u32 s48, 0x300
	s_cbranch_scc0 .Lq_other
	s_and_b32 s101, s48, 1
	s_lshr_b32 s48, s48, 1
	s_branch .Lq_done
.Lq_other:
	s_sub_i32 s48, s48, 0x180
.Lq_done:
	s_cmp_ge_i32 s48, s52
	s_cbranch_scc1 .LBB0_440
	s_cmpk_gt_i32 s48, 0x17f
	s_cbranch_scc0 .LBB0_874
	s_cmpk_gt_u32 s48, 0x2ff
	s_cbranch_scc0 .LBB0_580
	s_cmpk_gt_u32 s48, 0x383
	s_cbranch_scc0 .LBB0_556
	v_readlane_b32 s0, v252, 15
	s_cmp_ge_i32 s48, s0
	s_mov_b64 s[0:1], -1
	s_cbranch_scc0 .LBB0_530
	v_readlane_b32 s0, v252, 15
	s_sub_i32 s2, s48, s0
	s_cmpk_gt_i32 s2, 0xff
	s_cselect_b64 s[14:15], -1, 0
	s_cmpk_lt_i32 s2, 0x100
	s_cselect_b64 s[6:7], -1, 0
	s_mov_b64 s[0:1], -1
	s_and_b64 vcc, exec, s[14:15]
	s_cbranch_vccnz .LBB0_450
	s_bfe_i32 s0, s2, 0x10002
	s_and_b32 s0, s0, 33
	s_ashr_i32 s1, s2, 3
	s_add_i32 s12, s0, s1
	s_mov_b64 s[0:1], 0

;     const int tid = opaque_tid(), lane = tid & 63, r32 = lane & 31, hi = lane >> 5; const int wid = __builtin_amdgcn_readfirstlane(tid >> 6);
;     const bf16_t* Qw = Q + (long)(wid * QBLK) * PITCH;
;     const unsigned lds0 = (unsigned)(uintptr_t)shm;
;     float* wsf = (float*)(shm + LDS_WS) + wid * 64;
;     const unsigned kvo = (unsigned)((lane * PITCH + wid * 8) * 2);
;     const unsigned vvo = (unsigned)(((16 * (wid & 3) + (lane >> 2)) * PITCH + (wid >> 2) * 32 + (lane & 3) * 8) * 2);
;     const unsigned kdst = lds0 + LDS_K + wid * 1024, vdst = lds0 + LDS_V + wid * 1024;
;     ...
;     const char* Kbase = shm + LDS_K; bf16x8 kf[8];
;     const lds_cptr shm3 = (lds_cptr)shm; const lds_cptr kp0 = shm3 + LDS_K + hi * 1024 + r32 * 16; const lds_cptr vp0 = shm3 + LDS_V + ((lane >> 4) & 1) * 32 + (lane & 3) * 8 + (4 * hi + ((lane & 15) >> 2)) * 64;
;     DMA_K(0, 0); DMA_V(0, 0); DMA_K(1, SLOTB);
;     bf16x8 qr[4];
; #pragma unroll
;     for (int d0 = 0; d0 < 4; ++d0) qr[d0] = *reinterpret_cast<const bf16x8*>(&Qw[(long)r32 * PITCH + d0 * 16 + hi * 8]);
;     float mhat = (MODE == 0) ? bref : 0.f, l_reg = 0.f; f32x16 o[2]; o[0] = f32x16{}; o[1] = f32x16{}; f32x16 negm = f32x16{};
;     if (MODE == 0) { _Pragma("unroll") for (int r = 0; r < 16; ++r) negm[r] = -bref; }
;     if (MODE != 1) asm volatile("" : "+v"(negm));
;     int na_gr = 0, na_rs = 0, na_qc = 0, na_cs = 0;
;     if (MODE == 1) { na_gr = r0 + (wid >> 1); na_rs = min(max(na_gr - 4, 0), 120); na_qc = 32 * (wid & 1) + r32; na_cs = min(max(na_qc - 8, 0), 48); }
;     ...
;     bool resc = false;
;     ...
;     f32x16 pA0, pA1, pB0, pB1;
;     int sl_prev = 0, sl_cur = 0, sl_next = SLOTB;
;     ...
;     DMA_K(2, 2 * SLOTB);
;     WAIT_BAR(3);
;     qkt(pA0, pA1, Kbase, qr, negm, r32, hi); asm volatile("s_nop 15\n\ts_nop 7" : "+v"(pA0), "+v"(pA1));
;     START(pA0, pA1);
;     _Pragma("unroll") for (int r = 0; r < 16; ++r) pA1[r] = __builtin_amdgcn_exp2f(pA1[r]);
;     WAIT_BAR(0);
; __global__ void __launch_bounds__(NTHREADS, 2) mega_fwd(Params P) {
;     ...
;                 if (idx < n_gqa) {
;                     const int qb = idx / 12, r12 = idx % 12, b = r12 / 6, h = r12 % 6; const size_t rb = (size_t)b * RPB;
;                     ap::unit<8, 0>(qkv + (rb + 256 * qb) * DIN + C_QC + 64 * h, qkv + rb * DIN + C_KC + 64 * (h / 3), qkv + rb * DIN + C_VC + 64 * (h / 3),
.LBB0_874:
	s_andn2_b64 vcc, exec, s[0:1]
	s_cbranch_vccnz .LBB0_439
	s_mul_hi_i32 s0, s48, 0x2aaaaaab
	s_lshr_b32 s1, s0, 31
	s_ashr_i32 s3, s0, 1
	s_add_i32 s3, s3, s1
	s_mul_i32 s0, s3, 12
	s_sub_i32 s0, s48, s0
	s_mul_i32 s1, s0, 43
	s_bfe_u32 s2, s1, 0x1000f
	s_bfe_u32 s1, s1, 0x80008
	s_add_i32 s1, s1, s2
	s_sext_i32_i8 s18, s1
	s_mul_i32 s1, s1, 6
	s_mul_i32 s9, s18, 0x2100
	s_lshl_b32 s4, s3, 8
	s_sub_i32 s8, s0, s1
	s_ashr_i32 s5, s9, 31
	s_ashr_i32 s6, s4, 31
	s_add_u32 s4, s9, s4
	s_addc_u32 s5, s5, s6
	s_mul_i32 s6, s5, 0x1200
	s_mul_hi_u32 s7, s4, 0x1200
	s_mov_b64 s[0:1], s[76:77]
	s_add_i32 s7, s7, s6
	s_mul_i32 s6, s4, 0x1200
	s_sext_i32_i8 s2, s8
	s_add_u32 s10, s0, s6
	s_addc_u32 s11, s1, s7
	s_lshl_b32 s0, s2, 6
	s_ashr_i32 s1, s0, 31
	s_lshl_b64 s[6:7], s[0:1], 1
	s_add_u32 s26, s10, s6
	s_addc_u32 s27, s11, s7
	s_mov_b64 s[0:1], s[76:77]
	s_mul_i32 s10, s18, 0x2520000
	s_mul_hi_i32 s9, s9, 0x1200
	s_mul_i32 s40, s101, 0x1290000
	s_add_u32 s10, s10, s40
	s_addc_u32 s9, s9, 0
	s_add_u32 s2, s0, s10
	s_addc_u32 s22, s1, s9
	s_bfe_i32 s0, s8, 0x80000
	s_mulk_i32 s0, 0x56
	s_bfe_u32 s1, s0, 0x1000f
	s_bfe_u32 s0, s0, 0x80008
	s_add_i32 s0, s0, s1
	s_sext_i32_i8 s0, s0
	s_lshl_b32 s0, s0, 6
	s_ashr_i32 s1, s0, 31
	s_lshl_b64 s[16:17], s[0:1], 1
	s_add_u32 s30, s2, s16
	s_addc_u32 s34, s22, s17
	s_add_u32 s14, s30, 0xe400300
	s_addc_u32 s15, s34, 0
	s_mov_b64 s[0:1], s[76:77]
	s_add_u32 s23, s0, s10
	s_addc_u32 s24, s1, s9
	s_add_u32 s35, s23, s16
	s_addc_u32 s36, s24, s17
	v_readlane_b32 s20, v252, 9
	s_add_u32 s12, s35, 0xe401100
	s_mov_b64 s[10:11], s[76:77]
	s_mov_b64 s[8:9], s[76:77]
	s_mov_b64 s[0:1], s[76:77]
	v_readlane_b32 s21, v252, 10
	s_addc_u32 s13, s36, 0
	s_lshl_b64 s[20:21], s[20:21], 2
	s_add_u32 s0, s0, s20
	s_addc_u32 s1, s1, s21
	v_mov_b32_e32 v0, s0
	s_mov_b32 s0, 0x184000
	v_mov_b32_e32 v3, s1
	v_add_co_u32_e32 v2, vcc, s0, v0
	v_mov_b32_e32 v194, 0
	s_nop 0
	v_addc_co_u32_e32 v3, vcc, 0, v3, vcc
	flat_load_dword v6, v[2:3]
	v_mov_b32 v14, v214
	s_waitcnt vmcnt(0) lgkmcnt(0)
	v_xor_b32_e32 v50, 0x80000000, v6
	v_readfirstlane_b32 s25, v14
	s_ashr_i32 s19, s25, 6
	s_lshl_b32 s0, s19, 5
	s_ashr_i32 s1, s0, 31
	s_mul_i32 s20, s19, 0x24000
	s_mul_hi_i32 s21, s0, 0x1200
	s_add_u32 s28, s26, s20
	s_addc_u32 s29, s27, s21
	s_lshl_b32 s20, s19, 4
	v_and_b32_e32 v15, 63, v14
	v_mov_b32_e32 v0, s20
	v_mad_u32_u24 v193, v15, s80, v0
	v_bfe_u32 v0, v14, 2, 4
	v_and_or_b32 v0, s20, 48, v0
	s_ashr_i32 s20, s25, 3
	s_and_b32 s20, s20, 0x7fffffe0
	v_mov_b32_e32 v2, s20
	v_mad_u32_u24 v0, v0, s81, v2
	v_lshlrev_b32_e32 v2, 3, v14
	v_and_b32_e32 v187, 24, v2
	v_and_b32_e32 v17, 31, v14
	v_or_b32_e32 v0, v0, v187
	s_lshl_b32 s21, s19, 10
	v_lshlrev_b32_e32 v192, 1, v0
	s_cmp_lg_u32 0, -1
	v_mul_u32_u24_e32 v0, 0x900, v17
	v_bfe_u32 v186, v14, 5, 1
	s_cselect_b32 s20, 0, 0
	v_lshlrev_b32_e32 v0, 1, v0
	s_add_i32 s26, s21, s20
	v_lshl_or_b32 v0, v186, 4, v0
	s_add_i32 s20, s26, 0x6000
	s_mov_b32 s27, m0
	s_mov_b32 m0, s26
	s_nop 0
	global_load_lds_dwordx4 v193, s[14:15]
	s_mov_b32 m0, s27
	v_lshl_add_u64 v[2:3], s[28:29], 0, v[0:1]
	s_mov_b32 s27, m0
	s_mov_b32 m0, s20
	s_nop 0
	global_load_lds_dwordx4 v192, s[12:13]
	s_mov_b32 m0, s27
	s_add_u32 s38, s30, 0xe448300
	v_add_co_u32_e32 v4, vcc, s82, v2
	s_addc_u32 s39, s34, 0
	s_add_i32 s27, s26, 0x2000
	s_mov_b32 s31, m0
	s_mov_b32 m0, s27
	s_nop 0
	global_load_lds_dwordx4 v193, s[38:39]
	s_mov_b32 m0, s31
	v_addc_co_u32_e32 v5, vcc, 0, v3, vcc
	flat_load_dwordx4 v[162:165], v[4:5]
	s_mov_b64 s[28:29], 0xe400000
	v_lshl_add_u64 v[2:3], v[2:3], 0, s[28:29]
	flat_load_dwordx4 v[158:161], v[2:3] offset:32
	flat_load_dwordx4 v[154:157], v[2:3] offset:64
	flat_load_dwordx4 v[150:153], v[2:3] offset:96
	v_mov_b32_e32 v51, v50
	v_mov_b32_e32 v52, v50
	v_mov_b32_e32 v53, v50
	v_mov_b32_e32 v54, v50
	v_mov_b32_e32 v55, v50
	v_mov_b32_e32 v56, v50
	v_mov_b32_e32 v57, v50
	v_mov_b32_e32 v58, v50
	v_mov_b32_e32 v59, v50
	v_mov_b32_e32 v60, v50
	v_mov_b32_e32 v61, v50
	v_mov_b32_e32 v62, v50
	v_mov_b32_e32 v63, v50
	v_mov_b32_e32 v64, v50
	v_mov_b32_e32 v65, v50
	s_add_u32 s28, s30, 0xe490300
	v_lshlrev_b32_e32 v0, 10, v186
	v_lshlrev_b32_e32 v4, 4, v17
	s_addc_u32 s29, s34, 0
	s_add_i32 s27, s26, 0x4000
	s_mov_b32 s31, m0
	s_mov_b32 m0, s27
	s_nop 0
	global_load_lds_dwordx4 v193, s[28:29]
	s_mov_b32 m0, s31
	v_add3_u32 v191, 0, v0, v4
	s_waitcnt vmcnt(3) lgkmcnt(0)
	s_barrier
	ds_read_b128 v[2:5], v191
	ds_read_b128 v[6:9], v191 offset:512
	s_waitcnt vmcnt(0) lgkmcnt(0)
	v_mfma_f32_32x32x16_bf16 v[34:49], v[2:5], v[162:165], v[50:65]
	s_add_u32 s38, s30, 0xe4d8300
	s_addc_u32 s39, s34, 0
	s_add_u32 s34, s35, 0xe449100
	s_addc_u32 s35, s36, 0
	v_lshlrev_b32_e32 v0, 1, v14
	v_and_b32_e32 v188, 32, v0
	v_lshlrev_b32_e32 v0, 8, v186
	v_mfma_f32_32x32x16_bf16 v[18:33], v[6:9], v[162:165], v[50:65]
	ds_read_b128 v[2:5], v191 offset:2048
	ds_read_b128 v[6:9], v191 offset:2560
	s_mov_b32 s31, 0
	s_mov_b32 s27, -1
	s_movk_i32 s29, 0x2000
	s_movk_i32 s28, 0x4000
	s_waitcnt lgkmcnt(1)
	v_mfma_f32_32x32x16_bf16 v[34:49], v[2:5], v[158:161], v[34:49]
	s_waitcnt lgkmcnt(0)
	v_mfma_f32_32x32x16_bf16 v[18:33], v[6:9], v[158:161], v[18:33]
	ds_read_b128 v[2:5], v191 offset:4096
	ds_read_b128 v[6:9], v191 offset:4608
	s_waitcnt lgkmcnt(1)
	v_mfma_f32_32x32x16_bf16 v[34:49], v[2:5], v[154:157], v[34:49]
	s_waitcnt lgkmcnt(0)
	v_mfma_f32_32x32x16_bf16 v[18:33], v[6:9], v[154:157], v[18:33]
	ds_read_b128 v[2:5], v191 offset:6144
	ds_read_b128 v[6:9], v191 offset:6656
	s_waitcnt lgkmcnt(1)
	v_mfma_f32_32x32x16_bf16 v[34:49], v[2:5], v[150:153], v[34:49]
	v_lshlrev_b32_e32 v3, 4, v14
	v_add_u32_e32 v2, 0, v188
	v_and_or_b32 v189, v3, s83, v0
	v_add3_u32 v190, v2, v187, v189
	s_waitcnt lgkmcnt(0)
	v_mfma_f32_32x32x16_bf16 v[18:33], v[6:9], v[150:153], v[18:33]
	s_nop 15
	s_nop 7
	s_waitcnt vmcnt(0) lgkmcnt(0)
	s_barrier
; #define WAIT_BAR(N) asm volatile("s_waitcnt vmcnt(" #N ") lgkmcnt(0)\n\ts_barrier" ::: "memory")
; #define DMA_K(t, slot) glds16s(kvo, Kh + (long)TROW(t) * PITCH, (unsigned)__builtin_amdgcn_readfirstlane(kdst + (slot)))
; #define DMA_V(t, slot) glds16s(vvo, Vh + (long)TROW(t) * PITCH, (unsigned)__builtin_amdgcn_readfirstlane(vdst + (slot)))
; #define RESC() do { if (resc) { asm volatile("s_waitcnt lgkmcnt(0)" ::: "memory"); \
;       _Pragma("unroll") for (int d_ = 0; d_ < 2; ++d_) _Pragma("unroll") for (int r = 0; r < 16; ++r) o[d_][r] *= wsf[crow(r, hi)]; } } while (0)
; #define ROT() do { sl_prev = sl_cur; sl_cur = sl_next; sl_next = (sl_next == (NSLOT - 1) * SLOTB) ? 0 : sl_next + SLOTB; } while (0)
;     ...
;     DMA_K(2, 2 * SLOTB);
;     WAIT_BAR(3);
;     qkt(pA0, pA1, Kbase, qr, negm, r32, hi); asm volatile("s_nop 15\n\ts_nop 7" : "+v"(pA0), "+v"(pA1));
;     START(pA0, pA1);
;     _Pragma("unroll") for (int r = 0; r < 16; ++r) pA1[r] = __builtin_amdgcn_exp2f(pA1[r]);
;     WAIT_BAR(0);
;     DMA_K(3, 0); DMA_V(1, SLOTB);
;     ROT();
;     kload8(kf, kp0 + sl_cur);
;     WAIT_BAR(2);
;     s16x4 vlo[8], vhi[8]; u32x4 pw0, pw1, pw2, pw3;
;     ...
;     int t = 1;
;     for (; t + 5 < NT; t += 2) {
;         STEP(pB0, pB1, pA0, pA1, t, true, true, true);     WAIT_BAR(2); RESC(); ROT();
;         STEP(pA0, pA1, pB0, pB1, t + 1, true, true, true); WAIT_BAR(2); RESC(); ROT();
	s_mov_b32 s30, m0
	s_mov_b32 m0, s26
	s_nop 0
	global_load_lds_dwordx4 v193, s[38:39]
	s_mov_b32 m0, s30
	s_add_i32 s30, s26, 0x8000
	s_mov_b32 s36, m0
	s_mov_b32 m0, s30
	s_nop 0
	global_load_lds_dwordx4 v192, s[34:35]
	s_mov_b32 m0, s36
	ds_read_b128 v[98:101], v191 offset:8192
	ds_read_b128 v[170:173], v191 offset:8704
	ds_read_b128 v[174:177], v191 offset:10240
	ds_read_b128 v[166:169], v191 offset:10752
	ds_read_b128 v[142:145], v191 offset:12288
	ds_read_b128 v[138:141], v191 offset:12800
	ds_read_b128 v[134:137], v191 offset:14336
	ds_read_b128 v[130:133], v191 offset:14848
	v_exp_f32_e32 v82, v34
	v_exp_f32_e32 v83, v35
	v_exp_f32_e32 v84, v36
	v_exp_f32_e32 v85, v37
	v_exp_f32_e32 v86, v38
	v_exp_f32_e32 v87, v39
	v_exp_f32_e32 v88, v40
	v_exp_f32_e32 v89, v41
	v_exp_f32_e32 v90, v42
	v_exp_f32_e32 v91, v43
	v_exp_f32_e32 v92, v44
	v_exp_f32_e32 v93, v45
	v_exp_f32_e32 v94, v46
	v_exp_f32_e32 v95, v47
	v_exp_f32_e32 v96, v48
	v_exp_f32_e32 v97, v49
	v_exp_f32_e32 v66, v18
	v_exp_f32_e32 v67, v19
	v_exp_f32_e32 v68, v20
	v_exp_f32_e32 v69, v21
	v_exp_f32_e32 v70, v22
	v_exp_f32_e32 v71, v23
	v_exp_f32_e32 v72, v24
	v_exp_f32_e32 v73, v25
	v_exp_f32_e32 v74, v26
	v_exp_f32_e32 v75, v27
	v_exp_f32_e32 v76, v28
	v_exp_f32_e32 v77, v29
	v_exp_f32_e32 v78, v30
	v_exp_f32_e32 v79, v31
	v_exp_f32_e32 v80, v32
	v_exp_f32_e32 v81, v33
	s_waitcnt vmcnt(2) lgkmcnt(0)
	s_barrier
	v_mov_b32_e32 v18, 0
	v_mov_b32_e32 v19, v194
	v_mov_b32_e32 v20, v194
	v_mov_b32_e32 v21, v194
	v_mov_b32_e32 v22, v194
	v_mov_b32_e32 v23, v194
	v_mov_b32_e32 v24, v194
	v_mov_b32_e32 v25, v194
	v_mov_b32_e32 v26, v194
	v_mov_b32_e32 v27, v194
	v_mov_b32_e32 v28, v194
	v_mov_b32_e32 v29, v194
	v_mov_b32_e32 v30, v194
	v_mov_b32_e32 v31, v194
	v_mov_b32_e32 v32, v194
	v_mov_b32_e32 v33, v194
	v_mov_b32_e32 v34, 0
	v_mov_b32_e32 v35, v194
	v_mov_b32_e32 v36, v194
	v_mov_b32_e32 v37, v194
	v_mov_b32_e32 v38, v194
	v_mov_b32_e32 v39, v194
	v_mov_b32_e32 v40, v194
	v_mov_b32_e32 v41, v194
	v_mov_b32_e32 v42, v194
	v_mov_b32_e32 v43, v194
	v_mov_b32_e32 v44, v194
	v_mov_b32_e32 v45, v194
	v_mov_b32_e32 v46, v194
	v_mov_b32_e32 v47, v194
	v_mov_b32_e32 v48, v194
	v_mov_b32_e32 v49, v194
.LBB0_876:
	v_add_u32_e32 v195, s31, v190
	ds_read_b64_tr_b16 v[182:183], v195 offset:24576
	ds_read_b64_tr_b16 v[184:185], v195 offset:25088
	v_add_f32_e32 v2, v82, v83
	v_add_f32_e32 v2, v84, v2
	v_add_f32_e32 v2, v85, v2
	v_add_f32_e32 v2, v86, v2
	v_add_f32_e32 v2, v87, v2
	v_cvt_pk_bf16_f32 v146, v82, v83
	v_cvt_pk_bf16_f32 v147, v84, v85
	s_waitcnt lgkmcnt(9)
	v_mfma_f32_32x32x16_bf16 v[114:129], v[98:101], v[162:165], v[50:65]
	ds_read_b64_tr_b16 v[178:179], v195 offset:28672
	ds_read_b64_tr_b16 v[180:181], v195 offset:29184
	s_waitcnt lgkmcnt(10)
	v_mfma_f32_32x32x16_bf16 v[98:113], v[170:173], v[162:165], v[50:65]
	v_add_f32_e32 v2, v88, v2
	v_add_f32_e32 v2, v89, v2
	v_add_f32_e32 v2, v90, v2
	v_add_f32_e32 v2, v91, v2
	v_cvt_pk_bf16_f32 v148, v86, v87
	v_cvt_pk_bf16_f32 v149, v88, v89
	ds_read_b64_tr_b16 v[82:83], v195 offset:25600
	ds_read_b64_tr_b16 v[84:85], v195 offset:26112
	v_add_f32_e32 v2, v92, v2
	v_add_f32_e32 v2, v93, v2
	v_add_f32_e32 v2, v94, v2
	v_add_f32_e32 v2, v95, v2
	v_cvt_pk_bf16_f32 v10, v90, v91
	v_cvt_pk_bf16_f32 v11, v92, v93
	s_waitcnt lgkmcnt(11)
	v_mfma_f32_32x32x16_bf16 v[114:129], v[174:177], v[158:161], v[114:129]
	ds_read_b64_tr_b16 v[86:87], v195 offset:29696
	ds_read_b64_tr_b16 v[88:89], v195 offset:30208
	s_waitcnt lgkmcnt(12)
	v_mfma_f32_32x32x16_bf16 v[98:113], v[166:169], v[158:161], v[98:113]
	v_add_f32_e32 v2, v96, v2
	v_add_f32_e32 v2, v97, v2
	v_add_f32_e32 v2, v66, v2
	v_add_f32_e32 v2, v67, v2
	v_cvt_pk_bf16_f32 v12, v94, v95
	v_cvt_pk_bf16_f32 v13, v96, v97
	ds_read_b64_tr_b16 v[90:91], v195 offset:26624
	ds_read_b64_tr_b16 v[92:93], v195 offset:27136
	v_add_f32_e32 v2, v68, v2
	v_add_f32_e32 v2, v69, v2
	v_add_f32_e32 v2, v70, v2
	v_add_f32_e32 v2, v71, v2
	v_cvt_pk_bf16_f32 v6, v66, v67
	v_cvt_pk_bf16_f32 v7, v68, v69
	s_waitcnt lgkmcnt(13)
	v_mfma_f32_32x32x16_bf16 v[114:129], v[142:145], v[154:157], v[114:129]
	ds_read_b64_tr_b16 v[66:67], v195 offset:30720
	ds_read_b64_tr_b16 v[68:69], v195 offset:31232
	s_waitcnt lgkmcnt(14)
	v_mfma_f32_32x32x16_bf16 v[98:113], v[138:141], v[154:157], v[98:113]
	v_add_f32_e32 v2, v72, v2
	v_add_f32_e32 v2, v73, v2
	v_add_f32_e32 v2, v74, v2
	v_add_f32_e32 v2, v75, v2
	v_cvt_pk_bf16_f32 v8, v70, v71
	v_cvt_pk_bf16_f32 v9, v72, v73
	ds_read_b64_tr_b16 v[70:71], v195 offset:27648
	ds_read_b64_tr_b16 v[72:73], v195 offset:28160
	v_add_f32_e32 v2, v76, v2
	v_add_f32_e32 v2, v77, v2
	v_add_f32_e32 v2, v78, v2
	v_add_f32_e32 v94, v79, v2
	v_cvt_pk_bf16_f32 v2, v74, v75
	v_cvt_pk_bf16_f32 v3, v76, v77
	s_waitcnt lgkmcnt(14)
	v_mfma_f32_32x32x16_bf16 v[114:129], v[134:137], v[150:153], v[114:129]
	ds_read_b64_tr_b16 v[74:75], v195 offset:31744
	ds_read_b64_tr_b16 v[76:77], v195 offset:32256
	v_mfma_f32_32x32x16_bf16 v[98:113], v[130:133], v[150:153], v[98:113]
	v_add_f32_e32 v4, v80, v94
	v_add_f32_e32 v4, v81, v4
	v_add_f32_e32 v195, 0, v4
	v_cvt_pk_bf16_f32 v4, v78, v79
	v_cvt_pk_bf16_f32 v5, v80, v81
	s_add_u32 s31, s2, s16
	s_addc_u32 s34, s22, s17
	s_add_u32 s36, s31, 0xe520300
	s_addc_u32 s37, s34, 0
	s_add_i32 s30, s29, s26
	s_mov_b32 s35, m0
	s_mov_b32 m0, s30
	s_nop 0
	global_load_lds_dwordx4 v193, s[36:37]
	s_mov_b32 m0, s35
	s_add_u32 s35, s23, s16
	s_addc_u32 s36, s24, s17
	s_add_u32 s38, s35, 0xe491100
	s_addc_u32 s39, s36, 0
	s_add_i32 s30, s28, s20
	s_mov_b32 s37, m0
	s_mov_b32 m0, s30
	s_nop 0
	global_load_lds_dwordx4 v192, s[38:39]
	s_mov_b32 m0, s37
	s_waitcnt lgkmcnt(14)
; #define WAIT_BAR(N) asm volatile("s_waitcnt vmcnt(" #N ") lgkmcnt(0)\n\ts_barrier" ::: "memory")
; #define RESC() do { if (resc) { asm volatile("s_waitcnt lgkmcnt(0)" ::: "memory"); \
;       _Pragma("unroll") for (int d_ = 0; d_ < 2; ++d_) _Pragma("unroll") for (int r = 0; r < 16; ++r) o[d_][r] *= wsf[crow(r, hi)]; } } while (0)
; #define ROT() do { sl_prev = sl_cur; sl_cur = sl_next; sl_next = (sl_next == (NSLOT - 1) * SLOTB) ? 0 : sl_next + SLOTB; } while (0)
;     ...
;     int t = 1;
;     for (; t + 5 < NT; t += 2) {
;         STEP(pB0, pB1, pA0, pA1, t, true, true, true);     WAIT_BAR(2); RESC(); ROT();
;         STEP(pA0, pA1, pB0, pB1, t + 1, true, true, true); WAIT_BAR(2); RESC(); ROT();
	v_mfma_f32_32x32x16_bf16 v[18:33], v[146:149], v[182:185], v[18:33]
	v_exp_f32_e32 v114, v114
	v_exp_f32_e32 v115, v115
	v_exp_f32_e32 v116, v116
	v_exp_f32_e32 v117, v117
	s_waitcnt lgkmcnt(12)
	v_mfma_f32_32x32x16_bf16 v[34:49], v[146:149], v[178:181], v[34:49]
	v_exp_f32_e32 v118, v118
	v_exp_f32_e32 v119, v119
	v_exp_f32_e32 v120, v120
	v_exp_f32_e32 v121, v121
	v_add_u32_e32 v94, s28, v191
	ds_read_b128 v[78:81], v94
	ds_read_b128 v[134:137], v94 offset:512
	s_waitcnt lgkmcnt(12)
	v_mfma_f32_32x32x16_bf16 v[18:33], v[10:13], v[82:85], v[18:33]
	v_exp_f32_e32 v122, v122
	v_exp_f32_e32 v123, v123
	v_exp_f32_e32 v124, v124
	v_exp_f32_e32 v125, v125
	ds_read_b128 v[138:141], v94 offset:2048
	ds_read_b128 v[142:145], v94 offset:2560
	s_waitcnt lgkmcnt(12)
	v_mfma_f32_32x32x16_bf16 v[34:49], v[10:13], v[86:89], v[34:49]
	v_exp_f32_e32 v126, v126
	v_exp_f32_e32 v127, v127
	v_exp_f32_e32 v128, v128
	v_exp_f32_e32 v129, v129
	ds_read_b128 v[166:169], v94 offset:4096
	ds_read_b128 v[170:173], v94 offset:4608
	s_waitcnt lgkmcnt(12)
	v_mfma_f32_32x32x16_bf16 v[18:33], v[6:9], v[90:93], v[18:33]
	v_exp_f32_e32 v98, v98
	v_exp_f32_e32 v99, v99
	v_exp_f32_e32 v100, v100
	v_exp_f32_e32 v101, v101
	ds_read_b128 v[174:177], v94 offset:6144
	ds_read_b128 v[130:133], v94 offset:6656
	s_waitcnt lgkmcnt(12)
	v_mfma_f32_32x32x16_bf16 v[34:49], v[6:9], v[66:69], v[34:49]
	v_exp_f32_e32 v102, v102
	v_exp_f32_e32 v103, v103
	v_exp_f32_e32 v104, v104
	v_exp_f32_e32 v105, v105
	s_waitcnt lgkmcnt(10)
	v_mfma_f32_32x32x16_bf16 v[18:33], v[2:5], v[70:73], v[18:33]
	v_exp_f32_e32 v106, v106
	v_exp_f32_e32 v107, v107
	v_exp_f32_e32 v108, v108
	v_exp_f32_e32 v109, v109
	s_waitcnt lgkmcnt(8)
	v_mfma_f32_32x32x16_bf16 v[34:49], v[2:5], v[74:77], v[34:49]
	v_exp_f32_e32 v110, v110
	v_exp_f32_e32 v111, v111
	v_exp_f32_e32 v112, v112
	v_exp_f32_e32 v113, v113
	s_waitcnt vmcnt(2) lgkmcnt(0)
	s_barrier
	s_add_i32 s30, s28, 0x2000
	s_cmpk_lg_i32 s28, 0x4000
	s_cselect_b32 s30, s30, 0
	v_add_u32_e32 v196, s29, v190
	ds_read_b64_tr_b16 v[178:179], v196 offset:24576
	ds_read_b64_tr_b16 v[180:181], v196 offset:25088
	s_waitcnt lgkmcnt(9)
	v_mfma_f32_32x32x16_bf16 v[82:97], v[78:81], v[162:165], v[50:65]
	v_add_f32_e32 v2, v114, v115
	v_add_f32_e32 v2, v116, v2
	v_add_f32_e32 v2, v117, v2
	v_add_f32_e32 v2, v118, v2
	v_add_f32_e32 v2, v119, v2
	v_cvt_pk_bf16_f32 v146, v114, v115
	v_cvt_pk_bf16_f32 v147, v116, v117
	ds_read_b64_tr_b16 v[182:183], v196 offset:28672
	ds_read_b64_tr_b16 v[184:185], v196 offset:29184
	s_waitcnt lgkmcnt(10)
	v_mfma_f32_32x32x16_bf16 v[66:81], v[134:137], v[162:165], v[50:65]
	v_add_f32_e32 v2, v120, v2
	v_add_f32_e32 v2, v121, v2
	v_add_f32_e32 v2, v122, v2
	v_add_f32_e32 v2, v123, v2
	v_cvt_pk_bf16_f32 v148, v118, v119
	v_cvt_pk_bf16_f32 v149, v120, v121
	ds_read_b64_tr_b16 v[114:115], v196 offset:25600
	ds_read_b64_tr_b16 v[116:117], v196 offset:26112
	s_waitcnt lgkmcnt(11)
	v_mfma_f32_32x32x16_bf16 v[82:97], v[138:141], v[158:161], v[82:97]
	v_add_f32_e32 v2, v124, v2
	v_add_f32_e32 v2, v125, v2
	v_add_f32_e32 v2, v126, v2
	v_add_f32_e32 v2, v127, v2
	v_cvt_pk_bf16_f32 v10, v122, v123
	v_cvt_pk_bf16_f32 v11, v124, v125
	ds_read_b64_tr_b16 v[118:119], v196 offset:29696
	ds_read_b64_tr_b16 v[120:121], v196 offset:30208
	s_waitcnt lgkmcnt(12)
	v_mfma_f32_32x32x16_bf16 v[66:81], v[142:145], v[158:161], v[66:81]
	v_add_f32_e32 v2, v128, v2
	v_add_f32_e32 v2, v129, v2
	v_add_f32_e32 v2, v98, v2
	v_add_f32_e32 v2, v99, v2
	v_cvt_pk_bf16_f32 v12, v126, v127
	v_cvt_pk_bf16_f32 v13, v128, v129
	ds_read_b64_tr_b16 v[122:123], v196 offset:26624
	ds_read_b64_tr_b16 v[124:125], v196 offset:27136
	s_waitcnt lgkmcnt(13)
	v_mfma_f32_32x32x16_bf16 v[82:97], v[166:169], v[154:157], v[82:97]
	v_add_f32_e32 v2, v100, v2
	v_add_f32_e32 v2, v101, v2
	v_add_f32_e32 v2, v102, v2
	v_add_f32_e32 v2, v103, v2
	v_cvt_pk_bf16_f32 v6, v98, v99
	v_cvt_pk_bf16_f32 v7, v100, v101
	ds_read_b64_tr_b16 v[126:127], v196 offset:30720
	ds_read_b64_tr_b16 v[128:129], v196 offset:31232
	s_waitcnt lgkmcnt(14)
	v_mfma_f32_32x32x16_bf16 v[66:81], v[170:173], v[154:157], v[66:81]
	v_add_f32_e32 v2, v104, v2
	v_add_f32_e32 v2, v105, v2
	v_add_f32_e32 v2, v106, v2
	v_add_f32_e32 v2, v107, v2
	v_cvt_pk_bf16_f32 v8, v102, v103
	v_cvt_pk_bf16_f32 v9, v104, v105
	ds_read_b64_tr_b16 v[102:103], v196 offset:27648
	ds_read_b64_tr_b16 v[104:105], v196 offset:28160
	s_waitcnt lgkmcnt(14)
	v_mfma_f32_32x32x16_bf16 v[82:97], v[174:177], v[150:153], v[82:97]
	v_add_f32_e32 v2, v108, v2
	v_add_f32_e32 v2, v109, v2
	v_add_f32_e32 v2, v110, v2
	v_add_f32_e32 v98, v111, v2
	v_cvt_pk_bf16_f32 v2, v106, v107
	v_cvt_pk_bf16_f32 v3, v108, v109
	ds_read_b64_tr_b16 v[106:107], v196 offset:31744
	ds_read_b64_tr_b16 v[108:109], v196 offset:32256
	v_mfma_f32_32x32x16_bf16 v[66:81], v[130:133], v[150:153], v[66:81]
	v_add_f32_e32 v4, v112, v98
	v_add_f32_e32 v4, v113, v4
	v_add_f32_e32 v196, 0, v4
	v_cvt_pk_bf16_f32 v4, v110, v111
	v_cvt_pk_bf16_f32 v5, v112, v113
	s_add_u32 s38, s31, 0xe568300
	s_addc_u32 s39, s34, 0
	s_add_i32 s29, s28, s26
	s_mov_b32 s31, m0
	s_mov_b32 m0, s29
	s_nop 0
	global_load_lds_dwordx4 v193, s[38:39]
	s_mov_b32 m0, s31
	s_add_u32 s34, s35, 0xe4d9100
	s_addc_u32 s35, s36, 0
	s_add_i32 s29, s30, s20
	s_mov_b32 s31, m0
	s_mov_b32 m0, s29
	s_nop 0
	global_load_lds_dwordx4 v192, s[34:35]
	s_mov_b32 m0, s31
	s_waitcnt lgkmcnt(14)
	v_mfma_f32_32x32x16_bf16 v[18:33], v[146:149], v[178:181], v[18:33]
	v_exp_f32_e32 v82, v82
	v_exp_f32_e32 v83, v83
	v_exp_f32_e32 v84, v84
	v_exp_f32_e32 v85, v85
	s_waitcnt lgkmcnt(12)
; #define WAIT_BAR(N) asm volatile("s_waitcnt vmcnt(" #N ") lgkmcnt(0)\n\ts_barrier" ::: "memory")
; #define RESC() do { if (resc) { asm volatile("s_waitcnt lgkmcnt(0)" ::: "memory"); \
;       _Pragma("unroll") for (int d_ = 0; d_ < 2; ++d_) _Pragma("unroll") for (int r = 0; r < 16; ++r) o[d_][r] *= wsf[crow(r, hi)]; } } while (0)
; #define ROT() do { sl_prev = sl_cur; sl_cur = sl_next; sl_next = (sl_next == (NSLOT - 1) * SLOTB) ? 0 : sl_next + SLOTB; } while (0)
; #define ENDW(tt) do { if ((tt) + 3 < NT) { WAIT_BAR(2); } else if ((tt) + 2 < NT) { WAIT_BAR(1); } else { WAIT_BAR(0); } } while (0)
;     ...
;     int t = 1;
;     for (; t + 5 < NT; t += 2) {
;         STEP(pB0, pB1, pA0, pA1, t, true, true, true);     WAIT_BAR(2); RESC(); ROT();
;         STEP(pA0, pA1, pB0, pB1, t + 1, true, true, true); WAIT_BAR(2); RESC(); ROT();
;     }
;     ...
;     for (; t + 1 < NT; t += 2) {
;         STEP(pB0, pB1, pA0, pA1, t, (t + 3 < NT), (t + 1 < NT), (t + 1 < NT));         ENDW(t);     RESC(); ROT();
;         STEP(pA0, pA1, pB0, pB1, t + 1, (t + 4 < NT), (t + 2 < NT), (t + 2 < NT));     ENDW(t + 1); RESC(); ROT();
	v_mfma_f32_32x32x16_bf16 v[34:49], v[146:149], v[182:185], v[34:49]
	v_exp_f32_e32 v86, v86
	v_exp_f32_e32 v87, v87
	v_exp_f32_e32 v88, v88
	v_exp_f32_e32 v89, v89
	v_add_u32_e32 v110, s30, v191
	ds_read_b128 v[98:101], v110
	ds_read_b128 v[170:173], v110 offset:512
	s_waitcnt lgkmcnt(12)
	v_mfma_f32_32x32x16_bf16 v[18:33], v[10:13], v[114:117], v[18:33]
	v_exp_f32_e32 v90, v90
	v_exp_f32_e32 v91, v91
	v_exp_f32_e32 v92, v92
	v_exp_f32_e32 v93, v93
	ds_read_b128 v[174:177], v110 offset:2048
	ds_read_b128 v[166:169], v110 offset:2560
	s_waitcnt lgkmcnt(12)
	v_mfma_f32_32x32x16_bf16 v[34:49], v[10:13], v[118:121], v[34:49]
	v_exp_f32_e32 v94, v94
	v_exp_f32_e32 v95, v95
	v_exp_f32_e32 v96, v96
	v_exp_f32_e32 v97, v97
	ds_read_b128 v[142:145], v110 offset:4096
	ds_read_b128 v[138:141], v110 offset:4608
	s_waitcnt lgkmcnt(12)
	v_mfma_f32_32x32x16_bf16 v[18:33], v[6:9], v[122:125], v[18:33]
	v_exp_f32_e32 v66, v66
	v_exp_f32_e32 v67, v67
	v_exp_f32_e32 v68, v68
	v_exp_f32_e32 v69, v69
	ds_read_b128 v[134:137], v110 offset:6144
	ds_read_b128 v[130:133], v110 offset:6656
	s_waitcnt lgkmcnt(12)
	v_mfma_f32_32x32x16_bf16 v[34:49], v[6:9], v[126:129], v[34:49]
	v_exp_f32_e32 v70, v70
	v_exp_f32_e32 v71, v71
	v_exp_f32_e32 v72, v72
	v_exp_f32_e32 v73, v73
	s_waitcnt lgkmcnt(10)
	v_mfma_f32_32x32x16_bf16 v[18:33], v[2:5], v[102:105], v[18:33]
	v_exp_f32_e32 v74, v74
	v_exp_f32_e32 v75, v75
	v_exp_f32_e32 v76, v76
	v_exp_f32_e32 v77, v77
	s_waitcnt lgkmcnt(8)
	v_mfma_f32_32x32x16_bf16 v[34:49], v[2:5], v[106:109], v[34:49]
	v_exp_f32_e32 v78, v78
	v_exp_f32_e32 v79, v79
	v_exp_f32_e32 v80, v80
	v_exp_f32_e32 v81, v81
	s_add_i32 s34, s30, 0x2000
	s_cmpk_lg_i32 s30, 0x4000
	s_mov_b32 s31, s28
	s_cselect_b32 s28, s34, 0
	s_add_i32 s27, s27, 2
	s_add_u32 s23, s23, 0x90000
	s_addc_u32 s24, s24, 0
	s_waitcnt vmcnt(2) lgkmcnt(0)
	s_barrier
	s_add_u32 s2, s2, 0x90000
	v_add_f32_e32 v2, v194, v195
	s_addc_u32 s22, s22, 0
	s_mov_b32 s29, s30
	v_add_f32_e32 v194, v2, v196
	s_cmpk_gt_u32 s27, 0x3a
	s_cbranch_scc0 .LBB0_876
	s_and_b32 s2, s25, 0x3fffffc0
	s_lshl_b32 s2, s2, 2
	s_add_i32 s2, s2, 0
	ds_read_b64_tr_b16 v[182:183], v190 offset:24576
	ds_read_b64_tr_b16 v[184:185], v190 offset:25088
	v_add_f32_e32 v2, v82, v83
	v_add_f32_e32 v2, v84, v2
	v_add_f32_e32 v2, v85, v2
	v_add_f32_e32 v2, v86, v2
	v_add_f32_e32 v2, v87, v2
	v_cvt_pk_bf16_f32 v146, v82, v83
	v_cvt_pk_bf16_f32 v147, v84, v85
	s_waitcnt lgkmcnt(9)
	v_mfma_f32_32x32x16_bf16 v[114:129], v[98:101], v[162:165], v[50:65]
	ds_read_b64_tr_b16 v[178:179], v190 offset:28672
	ds_read_b64_tr_b16 v[180:181], v190 offset:29184
	v_add_f32_e32 v2, v88, v2
	v_add_f32_e32 v2, v89, v2
	v_add_f32_e32 v2, v90, v2
	v_add_f32_e32 v2, v91, v2
	v_cvt_pk_bf16_f32 v148, v86, v87
	v_cvt_pk_bf16_f32 v149, v88, v89
	s_waitcnt lgkmcnt(10)
	v_mfma_f32_32x32x16_bf16 v[98:113], v[170:173], v[162:165], v[50:65]
	ds_read_b64_tr_b16 v[82:83], v190 offset:25600
	ds_read_b64_tr_b16 v[84:85], v190 offset:26112
	v_add_f32_e32 v2, v92, v2
	v_add_f32_e32 v2, v93, v2
	v_add_f32_e32 v2, v94, v2
	v_add_f32_e32 v2, v95, v2
	v_cvt_pk_bf16_f32 v10, v90, v91
	v_cvt_pk_bf16_f32 v11, v92, v93
	s_waitcnt lgkmcnt(11)
	v_mfma_f32_32x32x16_bf16 v[114:129], v[174:177], v[158:161], v[114:129]
	ds_read_b64_tr_b16 v[86:87], v190 offset:29696
	ds_read_b64_tr_b16 v[88:89], v190 offset:30208
	v_add_f32_e32 v2, v96, v2
	v_add_f32_e32 v2, v97, v2
	v_add_f32_e32 v2, v66, v2
	v_add_f32_e32 v2, v67, v2
	v_cvt_pk_bf16_f32 v12, v94, v95
	v_cvt_pk_bf16_f32 v13, v96, v97
	s_waitcnt lgkmcnt(12)
	v_mfma_f32_32x32x16_bf16 v[98:113], v[166:169], v[158:161], v[98:113]
	ds_read_b64_tr_b16 v[90:91], v190 offset:26624
	ds_read_b64_tr_b16 v[92:93], v190 offset:27136
	v_add_f32_e32 v2, v68, v2
	v_add_f32_e32 v2, v69, v2
	v_add_f32_e32 v2, v70, v2
	v_add_f32_e32 v2, v71, v2
	v_cvt_pk_bf16_f32 v6, v66, v67
	v_cvt_pk_bf16_f32 v7, v68, v69
	s_waitcnt lgkmcnt(13)
	v_mfma_f32_32x32x16_bf16 v[114:129], v[142:145], v[154:157], v[114:129]
	ds_read_b64_tr_b16 v[66:67], v190 offset:30720
	ds_read_b64_tr_b16 v[68:69], v190 offset:31232
	v_add_f32_e32 v2, v72, v2
	v_add_f32_e32 v2, v73, v2
	v_add_f32_e32 v2, v74, v2
	v_add_f32_e32 v2, v75, v2
	v_cvt_pk_bf16_f32 v8, v70, v71
	v_cvt_pk_bf16_f32 v9, v72, v73
	s_waitcnt lgkmcnt(14)
	v_mfma_f32_32x32x16_bf16 v[98:113], v[138:141], v[154:157], v[98:113]
	ds_read_b64_tr_b16 v[70:71], v190 offset:27648
	ds_read_b64_tr_b16 v[72:73], v190 offset:28160
	v_add_f32_e32 v2, v76, v2
	v_add_f32_e32 v2, v77, v2
	v_add_f32_e32 v2, v78, v2
	v_add_f32_e32 v94, v79, v2
	v_cvt_pk_bf16_f32 v2, v74, v75
	v_cvt_pk_bf16_f32 v3, v76, v77
	s_waitcnt lgkmcnt(14)
	v_mfma_f32_32x32x16_bf16 v[114:129], v[134:137], v[150:153], v[114:129]
	ds_read_b64_tr_b16 v[74:75], v190 offset:31744
	ds_read_b64_tr_b16 v[76:77], v190 offset:32256
	v_add_f32_e32 v4, v80, v94
	v_add_f32_e32 v4, v81, v4
	v_add_f32_e32 v94, 0, v4
	v_cvt_pk_bf16_f32 v4, v78, v79
	v_cvt_pk_bf16_f32 v5, v80, v81
	v_mfma_f32_32x32x16_bf16 v[98:113], v[130:133], v[150:153], v[98:113]
	s_add_u32 s16, s14, 0x1200000
	s_addc_u32 s17, s15, 0
	s_cmp_lg_u32 0, -1
	s_cselect_b32 s23, 0, 0
	s_add_i32 s22, s23, s21
	s_add_i32 s24, s22, 0x2000
	s_mov_b32 s25, m0
	s_mov_b32 m0, s24
	s_nop 0
	global_load_lds_dwordx4 v193, s[16:17]
	s_mov_b32 m0, s25
	s_add_u32 s24, s12, 0x1170000
	s_addc_u32 s25, s13, 0
	s_add_i32 s16, s23, 0xa000
	s_add_i32 s17, s21, s16
	s_mov_b32 s21, m0
	s_mov_b32 m0, s17
	s_nop 0
	global_load_lds_dwordx4 v192, s[24:25]
	s_mov_b32 m0, s21
	v_add_f32_e32 v194, v194, v94
	s_waitcnt lgkmcnt(14)
	v_mfma_f32_32x32x16_bf16 v[18:33], v[146:149], v[182:185], v[18:33]
	v_exp_f32_e32 v114, v114
	v_exp_f32_e32 v115, v115
	v_exp_f32_e32 v116, v116
	v_exp_f32_e32 v117, v117
	s_waitcnt lgkmcnt(12)
; #define WAIT_BAR(N) asm volatile("s_waitcnt vmcnt(" #N ") lgkmcnt(0)\n\ts_barrier" ::: "memory")
; #define RESC() do { if (resc) { asm volatile("s_waitcnt lgkmcnt(0)" ::: "memory"); \
;       _Pragma("unroll") for (int d_ = 0; d_ < 2; ++d_) _Pragma("unroll") for (int r = 0; r < 16; ++r) o[d_][r] *= wsf[crow(r, hi)]; } } while (0)
; #define ROT() do { sl_prev = sl_cur; sl_cur = sl_next; sl_next = (sl_next == (NSLOT - 1) * SLOTB) ? 0 : sl_next + SLOTB; } while (0)
; #define ENDW(tt) do { if ((tt) + 3 < NT) { WAIT_BAR(2); } else if ((tt) + 2 < NT) { WAIT_BAR(1); } else { WAIT_BAR(0); } } while (0)
;     ...
;     int t = 1;
;     for (; t + 5 < NT; t += 2) {
;         STEP(pB0, pB1, pA0, pA1, t, true, true, true);     WAIT_BAR(2); RESC(); ROT();
;         STEP(pA0, pA1, pB0, pB1, t + 1, true, true, true); WAIT_BAR(2); RESC(); ROT();
;     }
;     ...
;     for (; t + 1 < NT; t += 2) {
;         STEP(pB0, pB1, pA0, pA1, t, (t + 3 < NT), (t + 1 < NT), (t + 1 < NT));         ENDW(t);     RESC(); ROT();
;         STEP(pA0, pA1, pB0, pB1, t + 1, (t + 4 < NT), (t + 2 < NT), (t + 2 < NT));     ENDW(t + 1); RESC(); ROT();
	v_mfma_f32_32x32x16_bf16 v[34:49], v[146:149], v[178:181], v[34:49]
	v_exp_f32_e32 v118, v118
	v_exp_f32_e32 v119, v119
	v_exp_f32_e32 v120, v120
	v_exp_f32_e32 v121, v121
	ds_read_b128 v[78:81], v191 offset:16384
	ds_read_b128 v[94:97], v191 offset:16896
	s_waitcnt lgkmcnt(12)
	v_mfma_f32_32x32x16_bf16 v[18:33], v[10:13], v[82:85], v[18:33]
	v_exp_f32_e32 v122, v122
	v_exp_f32_e32 v123, v123
	v_exp_f32_e32 v124, v124
	v_exp_f32_e32 v125, v125
	ds_read_b128 v[166:169], v191 offset:18432
	ds_read_b128 v[170:173], v191 offset:18944
	s_waitcnt lgkmcnt(12)
	v_mfma_f32_32x32x16_bf16 v[34:49], v[10:13], v[86:89], v[34:49]
	v_exp_f32_e32 v126, v126
	v_exp_f32_e32 v127, v127
	v_exp_f32_e32 v128, v128
	v_exp_f32_e32 v129, v129
	ds_read_b128 v[174:177], v191 offset:20480
	ds_read_b128 v[178:181], v191 offset:20992
	s_waitcnt lgkmcnt(12)
	v_mfma_f32_32x32x16_bf16 v[18:33], v[6:9], v[90:93], v[18:33]
	v_exp_f32_e32 v98, v98
	v_exp_f32_e32 v99, v99
	v_exp_f32_e32 v100, v100
	v_exp_f32_e32 v101, v101
	ds_read_b128 v[90:93], v191 offset:22528
	ds_read_b128 v[82:85], v191 offset:23040
	s_waitcnt lgkmcnt(12)
	v_mfma_f32_32x32x16_bf16 v[34:49], v[6:9], v[66:69], v[34:49]
	v_exp_f32_e32 v102, v102
	v_exp_f32_e32 v103, v103
	v_exp_f32_e32 v104, v104
	v_exp_f32_e32 v105, v105
	s_waitcnt lgkmcnt(10)
	v_mfma_f32_32x32x16_bf16 v[18:33], v[2:5], v[70:73], v[18:33]
	v_exp_f32_e32 v106, v106
	v_exp_f32_e32 v107, v107
	v_exp_f32_e32 v108, v108
	v_exp_f32_e32 v109, v109
	s_waitcnt lgkmcnt(8)
	v_mfma_f32_32x32x16_bf16 v[34:49], v[2:5], v[74:77], v[34:49]
	v_exp_f32_e32 v110, v110
	v_exp_f32_e32 v111, v111
	v_exp_f32_e32 v112, v112
	v_exp_f32_e32 v113, v113
	s_waitcnt vmcnt(2) lgkmcnt(0)
	s_barrier
	ds_read_b64_tr_b16 v[182:183], v190 offset:32768
	ds_read_b64_tr_b16 v[184:185], v190 offset:33280
	v_add_f32_e32 v2, v114, v115
	v_add_f32_e32 v2, v116, v2
	v_add_f32_e32 v2, v117, v2
	v_add_f32_e32 v2, v118, v2
	v_add_f32_e32 v2, v119, v2
	v_cvt_pk_bf16_f32 v146, v114, v115
	v_cvt_pk_bf16_f32 v147, v116, v117
	s_waitcnt lgkmcnt(9)
	v_mfma_f32_32x32x16_bf16 v[130:145], v[78:81], v[162:165], v[50:65]
	ds_read_b64_tr_b16 v[114:115], v190 offset:36864
	ds_read_b64_tr_b16 v[116:117], v190 offset:37376
	s_waitcnt lgkmcnt(10)
	v_mfma_f32_32x32x16_bf16 v[66:81], v[94:97], v[162:165], v[50:65]
	v_add_f32_e32 v2, v120, v2
	v_add_f32_e32 v2, v121, v2
	v_add_f32_e32 v2, v122, v2
	v_add_f32_e32 v2, v123, v2
	v_cvt_pk_bf16_f32 v148, v118, v119
	v_cvt_pk_bf16_f32 v149, v120, v121
	ds_read_b64_tr_b16 v[86:87], v190 offset:33792
	ds_read_b64_tr_b16 v[88:89], v190 offset:34304
	v_add_f32_e32 v2, v124, v2
	v_add_f32_e32 v2, v125, v2
	v_add_f32_e32 v2, v126, v2
	v_add_f32_e32 v2, v127, v2
	v_cvt_pk_bf16_f32 v10, v122, v123
	v_cvt_pk_bf16_f32 v11, v124, v125
	s_waitcnt lgkmcnt(11)
	v_mfma_f32_32x32x16_bf16 v[130:145], v[166:169], v[158:161], v[130:145]
	ds_read_b64_tr_b16 v[94:95], v190 offset:37888
	ds_read_b64_tr_b16 v[96:97], v190 offset:38400
	s_waitcnt lgkmcnt(12)
	v_mfma_f32_32x32x16_bf16 v[66:81], v[170:173], v[158:161], v[66:81]
	v_add_f32_e32 v2, v128, v2
	v_add_f32_e32 v2, v129, v2
	v_add_f32_e32 v2, v98, v2
	v_add_f32_e32 v2, v99, v2
	v_cvt_pk_bf16_f32 v12, v126, v127
	v_cvt_pk_bf16_f32 v13, v128, v129
	ds_read_b64_tr_b16 v[118:119], v190 offset:34816
	ds_read_b64_tr_b16 v[120:121], v190 offset:35328
	v_add_f32_e32 v2, v100, v2
	v_add_f32_e32 v2, v101, v2
	v_add_f32_e32 v2, v102, v2
	v_add_f32_e32 v2, v103, v2
	v_cvt_pk_bf16_f32 v6, v98, v99
	v_cvt_pk_bf16_f32 v7, v100, v101
	s_waitcnt lgkmcnt(13)
	v_mfma_f32_32x32x16_bf16 v[130:145], v[174:177], v[154:157], v[130:145]
	ds_read_b64_tr_b16 v[122:123], v190 offset:38912
	ds_read_b64_tr_b16 v[124:125], v190 offset:39424
	s_waitcnt lgkmcnt(14)
	v_mfma_f32_32x32x16_bf16 v[66:81], v[178:181], v[154:157], v[66:81]
	v_add_f32_e32 v2, v104, v2
	v_add_f32_e32 v2, v105, v2
	v_add_f32_e32 v2, v106, v2
	v_add_f32_e32 v2, v107, v2
	v_cvt_pk_bf16_f32 v8, v102, v103
	v_cvt_pk_bf16_f32 v9, v104, v105
	ds_read_b64_tr_b16 v[102:103], v190 offset:35840
	ds_read_b64_tr_b16 v[104:105], v190 offset:36352
	v_add_f32_e32 v2, v108, v2
	v_add_f32_e32 v2, v109, v2
	v_add_f32_e32 v2, v110, v2
	v_add_f32_e32 v98, v111, v2
	v_cvt_pk_bf16_f32 v2, v106, v107
	v_cvt_pk_bf16_f32 v3, v108, v109
	s_waitcnt lgkmcnt(14)
	v_mfma_f32_32x32x16_bf16 v[130:145], v[90:93], v[150:153], v[130:145]
	ds_read_b64_tr_b16 v[90:91], v190 offset:39936
	ds_read_b64_tr_b16 v[92:93], v190 offset:40448
	v_mfma_f32_32x32x16_bf16 v[66:81], v[82:85], v[150:153], v[66:81]
	v_add_f32_e32 v4, v112, v98
	v_add_f32_e32 v4, v113, v4
	v_add_f32_e32 v82, 0, v4
	v_cvt_pk_bf16_f32 v4, v110, v111
	v_cvt_pk_bf16_f32 v5, v112, v113
	s_add_u32 s14, s14, 0x1248000
	s_addc_u32 s15, s15, 0
	s_add_i32 s21, s22, 0x4000
	s_mov_b32 s23, m0
	s_mov_b32 m0, s21
	s_nop 0
	global_load_lds_dwordx4 v193, s[14:15]
	s_mov_b32 m0, s23
	s_add_u32 s14, s12, 0x11b8000
	s_addc_u32 s15, s13, 0
	s_mov_b32 s21, m0
	s_mov_b32 m0, s20
	s_nop 0
	global_load_lds_dwordx4 v192, s[14:15]
	s_mov_b32 m0, s21
	v_add_f32_e32 v194, v194, v82
	s_waitcnt lgkmcnt(14)
	v_mfma_f32_32x32x16_bf16 v[18:33], v[146:149], v[182:185], v[18:33]
	v_exp_f32_e32 v130, v130
	v_exp_f32_e32 v131, v131
	v_exp_f32_e32 v132, v132
	v_exp_f32_e32 v133, v133
	s_waitcnt lgkmcnt(12)
	v_mfma_f32_32x32x16_bf16 v[34:49], v[146:149], v[114:117], v[34:49]
	v_exp_f32_e32 v134, v134
	v_exp_f32_e32 v135, v135
	v_exp_f32_e32 v136, v136
	v_exp_f32_e32 v137, v137
	ds_read_b128 v[82:85], v191
	ds_read_b128 v[106:109], v191 offset:512
	s_waitcnt lgkmcnt(12)
	v_mfma_f32_32x32x16_bf16 v[18:33], v[10:13], v[86:89], v[18:33]
	v_exp_f32_e32 v138, v138
	v_exp_f32_e32 v139, v139
	v_exp_f32_e32 v140, v140
	v_exp_f32_e32 v141, v141
	ds_read_b128 v[110:113], v191 offset:2048
	ds_read_b128 v[166:169], v191 offset:2560
	s_waitcnt lgkmcnt(12)
	v_mfma_f32_32x32x16_bf16 v[34:49], v[10:13], v[94:97], v[34:49]
	v_exp_f32_e32 v142, v142
	v_exp_f32_e32 v143, v143
	v_exp_f32_e32 v144, v144
	v_exp_f32_e32 v145, v145
	ds_read_b128 v[170:173], v191 offset:4096
	ds_read_b128 v[174:177], v191 offset:4608
	s_waitcnt lgkmcnt(12)
	v_mfma_f32_32x32x16_bf16 v[18:33], v[6:9], v[118:121], v[18:33]
	v_exp_f32_e32 v66, v66
	v_exp_f32_e32 v67, v67
	v_exp_f32_e32 v68, v68
	v_exp_f32_e32 v69, v69
	ds_read_b128 v[178:181], v191 offset:6144
	ds_read_b128 v[98:101], v191 offset:6656
	s_waitcnt lgkmcnt(12)
	v_mfma_f32_32x32x16_bf16 v[34:49], v[6:9], v[122:125], v[34:49]
	v_exp_f32_e32 v70, v70
	v_exp_f32_e32 v71, v71
	v_exp_f32_e32 v72, v72
	v_exp_f32_e32 v73, v73
	s_waitcnt lgkmcnt(10)
	v_mfma_f32_32x32x16_bf16 v[18:33], v[2:5], v[102:105], v[18:33]
	v_exp_f32_e32 v74, v74
	v_exp_f32_e32 v75, v75
	v_exp_f32_e32 v76, v76
	v_exp_f32_e32 v77, v77
	s_waitcnt lgkmcnt(8)
	v_mfma_f32_32x32x16_bf16 v[34:49], v[2:5], v[90:93], v[34:49]
	v_exp_f32_e32 v78, v78
	v_exp_f32_e32 v79, v79
	v_exp_f32_e32 v80, v80
	v_exp_f32_e32 v81, v81
	s_waitcnt vmcnt(2) lgkmcnt(0)
	s_barrier
	ds_read_b64_tr_b16 v[102:103], v190 offset:40960
	ds_read_b64_tr_b16 v[104:105], v190 offset:41472
	v_add_f32_e32 v2, v130, v131
	v_add_f32_e32 v2, v132, v2
	v_add_f32_e32 v2, v133, v2
	v_add_f32_e32 v2, v134, v2
	v_add_f32_e32 v2, v135, v2
	v_cvt_pk_bf16_f32 v146, v130, v131
	v_cvt_pk_bf16_f32 v147, v132, v133
	s_waitcnt lgkmcnt(9)
	v_mfma_f32_32x32x16_bf16 v[114:129], v[82:85], v[162:165], v[50:65]
	ds_read_b64_tr_b16 v[130:131], v190 offset:45056
	ds_read_b64_tr_b16 v[132:133], v190 offset:45568
	v_add_f32_e32 v2, v136, v2
	v_add_f32_e32 v2, v137, v2
	v_add_f32_e32 v2, v138, v2
	v_add_f32_e32 v2, v139, v2
	v_cvt_pk_bf16_f32 v148, v134, v135
	v_cvt_pk_bf16_f32 v149, v136, v137
	s_waitcnt lgkmcnt(10)
	v_mfma_f32_32x32x16_bf16 v[82:97], v[106:109], v[162:165], v[50:65]
	ds_read_b64_tr_b16 v[106:107], v190 offset:41984
	ds_read_b64_tr_b16 v[108:109], v190 offset:42496
	v_add_f32_e32 v2, v140, v2
	v_add_f32_e32 v2, v141, v2
	v_add_f32_e32 v2, v142, v2
	v_add_f32_e32 v2, v143, v2
	v_cvt_pk_bf16_f32 v10, v138, v139
	v_cvt_pk_bf16_f32 v11, v140, v141
	s_waitcnt lgkmcnt(11)
	v_mfma_f32_32x32x16_bf16 v[114:129], v[110:113], v[158:161], v[114:129]
	ds_read_b64_tr_b16 v[110:111], v190 offset:46080
	ds_read_b64_tr_b16 v[112:113], v190 offset:46592
	v_add_f32_e32 v2, v144, v2
	v_add_f32_e32 v2, v145, v2
	v_add_f32_e32 v2, v66, v2
	v_add_f32_e32 v2, v67, v2
	v_cvt_pk_bf16_f32 v12, v142, v143
	v_cvt_pk_bf16_f32 v13, v144, v145
	s_waitcnt lgkmcnt(12)
	v_mfma_f32_32x32x16_bf16 v[82:97], v[166:169], v[158:161], v[82:97]
	ds_read_b64_tr_b16 v[134:135], v190 offset:43008
	ds_read_b64_tr_b16 v[136:137], v190 offset:43520
	v_add_f32_e32 v2, v68, v2
	v_add_f32_e32 v2, v69, v2
	v_add_f32_e32 v2, v70, v2
	v_add_f32_e32 v2, v71, v2
	v_cvt_pk_bf16_f32 v6, v66, v67
	v_cvt_pk_bf16_f32 v7, v68, v69
	s_waitcnt lgkmcnt(13)
	v_mfma_f32_32x32x16_bf16 v[114:129], v[170:173], v[154:157], v[114:129]
	ds_read_b64_tr_b16 v[66:67], v190 offset:47104
	ds_read_b64_tr_b16 v[68:69], v190 offset:47616
	v_add_f32_e32 v2, v72, v2
	v_add_f32_e32 v2, v73, v2
	v_add_f32_e32 v2, v74, v2
	v_add_f32_e32 v2, v75, v2
	v_cvt_pk_bf16_f32 v8, v70, v71
	v_cvt_pk_bf16_f32 v9, v72, v73
	s_waitcnt lgkmcnt(14)
	v_mfma_f32_32x32x16_bf16 v[82:97], v[174:177], v[154:157], v[82:97]
	ds_read_b64_tr_b16 v[70:71], v190 offset:44032
	ds_read_b64_tr_b16 v[72:73], v190 offset:44544
	v_add_f32_e32 v2, v76, v2
	v_add_f32_e32 v2, v77, v2
	v_add_f32_e32 v2, v78, v2
	v_add_f32_e32 v138, v79, v2
	v_cvt_pk_bf16_f32 v2, v74, v75
	v_cvt_pk_bf16_f32 v3, v76, v77
	s_waitcnt lgkmcnt(14)
	v_mfma_f32_32x32x16_bf16 v[114:129], v[178:181], v[150:153], v[114:129]
	ds_read_b64_tr_b16 v[74:75], v190 offset:48128
	ds_read_b64_tr_b16 v[76:77], v190 offset:48640
	v_add_f32_e32 v4, v80, v138
	v_add_f32_e32 v4, v81, v4
	v_mfma_f32_32x32x16_bf16 v[82:97], v[98:101], v[150:153], v[82:97]
	v_add_f32_e32 v98, 0, v4
	v_cvt_pk_bf16_f32 v4, v78, v79
	v_cvt_pk_bf16_f32 v5, v80, v81
	s_add_u32 s14, s12, 0x1200000
	s_addc_u32 s15, s13, 0
	s_add_i32 s22, s22, 0x8000
	s_mov_b32 s20, m0
	s_mov_b32 m0, s22
	s_nop 0
	global_load_lds_dwordx4 v192, s[14:15]
	s_mov_b32 m0, s20
	v_add_f32_e32 v182, v194, v98
	s_waitcnt lgkmcnt(14)
	v_mfma_f32_32x32x16_bf16 v[18:33], v[146:149], v[102:105], v[18:33]
	v_exp_f32_e32 v114, v114
	v_exp_f32_e32 v115, v115
	v_exp_f32_e32 v116, v116
	v_exp_f32_e32 v117, v117
	s_waitcnt lgkmcnt(12)
	v_mfma_f32_32x32x16_bf16 v[34:49], v[146:149], v[130:133], v[34:49]
	v_exp_f32_e32 v118, v118
	v_exp_f32_e32 v119, v119
	v_exp_f32_e32 v120, v120
	v_exp_f32_e32 v121, v121
	ds_read_b128 v[78:81], v191 offset:8192
	ds_read_b128 v[138:141], v191 offset:8704
	s_waitcnt lgkmcnt(12)
	v_mfma_f32_32x32x16_bf16 v[18:33], v[10:13], v[106:109], v[18:33]
	v_exp_f32_e32 v122, v122
	v_exp_f32_e32 v123, v123
	v_exp_f32_e32 v124, v124
	v_exp_f32_e32 v125, v125
	ds_read_b128 v[142:145], v191 offset:10240
	ds_read_b128 v[166:169], v191 offset:10752
	s_waitcnt lgkmcnt(12)
	v_mfma_f32_32x32x16_bf16 v[34:49], v[10:13], v[110:113], v[34:49]
	v_exp_f32_e32 v126, v126
	v_exp_f32_e32 v127, v127
	v_exp_f32_e32 v128, v128
	v_exp_f32_e32 v129, v129
	ds_read_b128 v[170:173], v191 offset:12288
	ds_read_b128 v[174:177], v191 offset:12800
	s_waitcnt lgkmcnt(12)
	v_mfma_f32_32x32x16_bf16 v[18:33], v[6:9], v[134:137], v[18:33]
	v_exp_f32_e32 v82, v82
	v_exp_f32_e32 v83, v83
	v_exp_f32_e32 v84, v84
	v_exp_f32_e32 v85, v85
	ds_read_b128 v[134:137], v191 offset:14336
	ds_read_b128 v[130:133], v191 offset:14848
	s_waitcnt lgkmcnt(12)
	v_mfma_f32_32x32x16_bf16 v[34:49], v[6:9], v[66:69], v[34:49]
	v_exp_f32_e32 v86, v86
	v_exp_f32_e32 v87, v87
	v_exp_f32_e32 v88, v88
	v_exp_f32_e32 v89, v89
	s_waitcnt lgkmcnt(10)
	v_mfma_f32_32x32x16_bf16 v[18:33], v[2:5], v[70:73], v[18:33]
	v_exp_f32_e32 v90, v90
	v_exp_f32_e32 v91, v91
	v_exp_f32_e32 v92, v92
	v_exp_f32_e32 v93, v93
	s_waitcnt lgkmcnt(8)
	v_mfma_f32_32x32x16_bf16 v[34:49], v[2:5], v[74:77], v[34:49]
	v_exp_f32_e32 v94, v94
	v_exp_f32_e32 v95, v95
	v_exp_f32_e32 v96, v96
	v_exp_f32_e32 v97, v97
	s_waitcnt vmcnt(1) lgkmcnt(0)
	s_barrier
	ds_read_b64_tr_b16 v[178:179], v190 offset:24576
	ds_read_b64_tr_b16 v[180:181], v190 offset:25088
	v_add_f32_e32 v2, v114, v115
	v_add_f32_e32 v2, v116, v2
	v_add_f32_e32 v2, v117, v2
	v_add_f32_e32 v2, v118, v2
	v_add_f32_e32 v2, v119, v2
	v_cvt_pk_bf16_f32 v146, v114, v115
	v_cvt_pk_bf16_f32 v147, v116, v117
	s_waitcnt lgkmcnt(9)
	v_mfma_f32_32x32x16_bf16 v[98:113], v[78:81], v[162:165], v[50:65]
	ds_read_b64_tr_b16 v[114:115], v190 offset:28672
	ds_read_b64_tr_b16 v[116:117], v190 offset:29184
	s_waitcnt lgkmcnt(10)
	v_mfma_f32_32x32x16_bf16 v[66:81], v[138:141], v[162:165], v[50:65]
	v_add_f32_e32 v2, v120, v2
	v_add_f32_e32 v2, v121, v2
	v_add_f32_e32 v2, v122, v2
	v_add_f32_e32 v2, v123, v2
	v_cvt_pk_bf16_f32 v148, v118, v119
	v_cvt_pk_bf16_f32 v149, v120, v121
	ds_read_b64_tr_b16 v[118:119], v190 offset:25600
	ds_read_b64_tr_b16 v[120:121], v190 offset:26112
	v_add_f32_e32 v2, v124, v2
	v_add_f32_e32 v2, v125, v2
	v_add_f32_e32 v2, v126, v2
	v_add_f32_e32 v2, v127, v2
	v_cvt_pk_bf16_f32 v10, v122, v123
	v_cvt_pk_bf16_f32 v11, v124, v125
	s_waitcnt lgkmcnt(11)
	v_mfma_f32_32x32x16_bf16 v[98:113], v[142:145], v[158:161], v[98:113]
	ds_read_b64_tr_b16 v[122:123], v190 offset:29696
	ds_read_b64_tr_b16 v[124:125], v190 offset:30208
	s_waitcnt lgkmcnt(12)
	v_mfma_f32_32x32x16_bf16 v[66:81], v[166:169], v[158:161], v[66:81]
	v_add_f32_e32 v2, v128, v2
	v_add_f32_e32 v2, v129, v2
	v_add_f32_e32 v2, v82, v2
	v_add_f32_e32 v2, v83, v2
	v_cvt_pk_bf16_f32 v12, v126, v127
	v_cvt_pk_bf16_f32 v13, v128, v129
	ds_read_b64_tr_b16 v[138:139], v190 offset:26624
	ds_read_b64_tr_b16 v[140:141], v190 offset:27136
	v_add_f32_e32 v2, v84, v2
	v_add_f32_e32 v2, v85, v2
	v_add_f32_e32 v2, v86, v2
	v_add_f32_e32 v2, v87, v2
	v_cvt_pk_bf16_f32 v6, v82, v83
	v_cvt_pk_bf16_f32 v7, v84, v85
	s_waitcnt lgkmcnt(13)
	v_mfma_f32_32x32x16_bf16 v[98:113], v[170:173], v[154:157], v[98:113]
	ds_read_b64_tr_b16 v[82:83], v190 offset:30720
	ds_read_b64_tr_b16 v[84:85], v190 offset:31232
	s_waitcnt lgkmcnt(14)
	v_mfma_f32_32x32x16_bf16 v[66:81], v[174:177], v[154:157], v[66:81]
	v_add_f32_e32 v2, v88, v2
	v_add_f32_e32 v2, v89, v2
	v_add_f32_e32 v2, v90, v2
	v_add_f32_e32 v2, v91, v2
	v_cvt_pk_bf16_f32 v8, v86, v87
	v_cvt_pk_bf16_f32 v9, v88, v89
	ds_read_b64_tr_b16 v[86:87], v190 offset:27648
	ds_read_b64_tr_b16 v[88:89], v190 offset:28160
	v_add_f32_e32 v2, v92, v2
	v_add_f32_e32 v2, v93, v2
	v_add_f32_e32 v2, v94, v2
	v_add_f32_e32 v126, v95, v2
	v_cvt_pk_bf16_f32 v2, v90, v91
	v_cvt_pk_bf16_f32 v3, v92, v93
	s_waitcnt lgkmcnt(14)
	v_mfma_f32_32x32x16_bf16 v[98:113], v[134:137], v[150:153], v[98:113]
	ds_read_b64_tr_b16 v[90:91], v190 offset:31744
	ds_read_b64_tr_b16 v[92:93], v190 offset:32256
	v_mfma_f32_32x32x16_bf16 v[66:81], v[130:133], v[150:153], v[66:81]
	v_add_f32_e32 v4, v96, v126
	v_add_f32_e32 v4, v97, v4
	v_add_f32_e32 v126, 0, v4
	v_cvt_pk_bf16_f32 v4, v94, v95
	v_cvt_pk_bf16_f32 v5, v96, v97
	s_add_u32 s12, s12, 0x1248000
	s_addc_u32 s13, s13, 0
	s_mov_b32 s14, m0
	s_mov_b32 m0, s17
	s_nop 0
	global_load_lds_dwordx4 v192, s[12:13]
	s_mov_b32 m0, s14
	v_add_f32_e32 v126, v182, v126
	s_waitcnt lgkmcnt(14)
	v_mfma_f32_32x32x16_bf16 v[18:33], v[146:149], v[178:181], v[18:33]
	v_exp_f32_e32 v98, v98
	v_exp_f32_e32 v99, v99
	v_exp_f32_e32 v100, v100
	v_exp_f32_e32 v101, v101
	s_waitcnt lgkmcnt(12)
	v_mfma_f32_32x32x16_bf16 v[34:49], v[146:149], v[114:117], v[34:49]
	v_exp_f32_e32 v102, v102
	v_exp_f32_e32 v103, v103
	v_exp_f32_e32 v104, v104
	v_exp_f32_e32 v105, v105
	ds_read_b128 v[128:131], v191 offset:16384
	ds_read_b128 v[132:135], v191 offset:16896
	s_waitcnt lgkmcnt(12)
	v_mfma_f32_32x32x16_bf16 v[18:33], v[10:13], v[118:121], v[18:33]
	v_exp_f32_e32 v106, v106
	v_exp_f32_e32 v107, v107
	v_exp_f32_e32 v108, v108
	v_exp_f32_e32 v109, v109
	ds_read_b128 v[142:145], v191 offset:18432
	ds_read_b128 v[166:169], v191 offset:18944
	s_waitcnt lgkmcnt(12)
	v_mfma_f32_32x32x16_bf16 v[34:49], v[10:13], v[122:125], v[34:49]
	v_exp_f32_e32 v110, v110
	v_exp_f32_e32 v111, v111
	v_exp_f32_e32 v112, v112
	v_exp_f32_e32 v113, v113
	ds_read_b128 v[170:173], v191 offset:20480
	ds_read_b128 v[174:177], v191 offset:20992
	s_waitcnt lgkmcnt(12)
	v_mfma_f32_32x32x16_bf16 v[18:33], v[6:9], v[138:141], v[18:33]
	v_exp_f32_e32 v66, v66
	v_exp_f32_e32 v67, v67
	v_exp_f32_e32 v68, v68
	v_exp_f32_e32 v69, v69
	ds_read_b128 v[136:139], v191 offset:22528
	ds_read_b128 v[122:125], v191 offset:23040
	s_waitcnt lgkmcnt(12)
	v_mfma_f32_32x32x16_bf16 v[34:49], v[6:9], v[82:85], v[34:49]
	v_exp_f32_e32 v70, v70
	v_exp_f32_e32 v71, v71
	v_exp_f32_e32 v72, v72
	v_exp_f32_e32 v73, v73
	s_waitcnt lgkmcnt(10)
	v_mfma_f32_32x32x16_bf16 v[18:33], v[2:5], v[86:89], v[18:33]
	v_exp_f32_e32 v74, v74
	v_exp_f32_e32 v75, v75
	v_exp_f32_e32 v76, v76
	v_exp_f32_e32 v77, v77
	s_waitcnt lgkmcnt(8)
	v_mfma_f32_32x32x16_bf16 v[34:49], v[2:5], v[90:93], v[34:49]
	v_exp_f32_e32 v78, v78
	v_exp_f32_e32 v79, v79
	v_exp_f32_e32 v80, v80
	v_exp_f32_e32 v81, v81
	s_waitcnt vmcnt(0) lgkmcnt(0)
	s_barrier
; #define RESC() do { if (resc) { asm volatile("s_waitcnt lgkmcnt(0)" ::: "memory"); \
;       _Pragma("unroll") for (int d_ = 0; d_ < 2; ++d_) _Pragma("unroll") for (int r = 0; r < 16; ++r) o[d_][r] *= wsf[crow(r, hi)]; } } while (0)
; #define PKW(P, B) cvtpk_s(P[B], P[B + 1])
;     ...
;     STEP(pB0, pB1, pA0, pA1, NT - 1, false, false, false); RESC();
;     { float sacc = pB0[0] + pB0[1]; _Pragma("unroll") for (int r = 2; r < 16; ++r) sacc += pB0[r]; _Pragma("unroll") for (int r = 0; r < 16; ++r) sacc += pB1[r]; l_reg += sacc;
;       pw0 = (u32x4){PKW(pB0, 0), PKW(pB0, 2), PKW(pB0, 4), PKW(pB0, 6)}; pw1 = (u32x4){PKW(pB0, 8), PKW(pB0, 10), PKW(pB0, 12), PKW(pB0, 14)}; pw2 = (u32x4){PKW(pB1, 0), PKW(pB1, 2), PKW(pB1, 4), PKW(pB1, 6)}; pw3 = (u32x4){PKW(pB1, 8), PKW(pB1, 10), PKW(pB1, 12), PKW(pB1, 14)};
	ds_read_b64_tr_b16 v[114:115], v190 offset:32768
	ds_read_b64_tr_b16 v[116:117], v190 offset:33280
	v_add_f32_e32 v2, v98, v99
	v_add_f32_e32 v2, v100, v2
	v_add_f32_e32 v2, v101, v2
	v_add_f32_e32 v2, v102, v2
	v_add_f32_e32 v2, v103, v2
	v_cvt_pk_bf16_f32 v146, v98, v99
	v_cvt_pk_bf16_f32 v147, v100, v101
	s_waitcnt lgkmcnt(9)
	v_mfma_f32_32x32x16_bf16 v[82:97], v[128:131], v[162:165], v[50:65]
	ds_read_b64_tr_b16 v[98:99], v190 offset:36864
	ds_read_b64_tr_b16 v[100:101], v190 offset:37376
	v_add_f32_e32 v2, v104, v2
	v_add_f32_e32 v2, v105, v2
	v_add_f32_e32 v2, v106, v2
	v_add_f32_e32 v2, v107, v2
	v_cvt_pk_bf16_f32 v148, v102, v103
	v_cvt_pk_bf16_f32 v149, v104, v105
	s_waitcnt lgkmcnt(10)
	v_mfma_f32_32x32x16_bf16 v[50:65], v[132:135], v[162:165], v[50:65]
	ds_read_b64_tr_b16 v[118:119], v190 offset:33792
	ds_read_b64_tr_b16 v[120:121], v190 offset:34304
	v_add_f32_e32 v2, v108, v2
	v_add_f32_e32 v2, v109, v2
	v_add_f32_e32 v2, v110, v2
	v_add_f32_e32 v2, v111, v2
	v_cvt_pk_bf16_f32 v10, v106, v107
	v_cvt_pk_bf16_f32 v11, v108, v109
	s_waitcnt lgkmcnt(11)
	v_mfma_f32_32x32x16_bf16 v[82:97], v[142:145], v[158:161], v[82:97]
	ds_read_b64_tr_b16 v[102:103], v190 offset:37888
	ds_read_b64_tr_b16 v[104:105], v190 offset:38400
	v_add_f32_e32 v2, v112, v2
	v_add_f32_e32 v2, v113, v2
	v_add_f32_e32 v2, v66, v2
	v_add_f32_e32 v2, v67, v2
	v_cvt_pk_bf16_f32 v12, v110, v111
	v_cvt_pk_bf16_f32 v13, v112, v113
	s_waitcnt lgkmcnt(12)
	v_mfma_f32_32x32x16_bf16 v[50:65], v[166:169], v[158:161], v[50:65]
	ds_read_b64_tr_b16 v[106:107], v190 offset:34816
	ds_read_b64_tr_b16 v[108:109], v190 offset:35328
	v_add_f32_e32 v2, v68, v2
	v_add_f32_e32 v2, v69, v2
	v_add_f32_e32 v2, v70, v2
	v_add_f32_e32 v2, v71, v2
	v_cvt_pk_bf16_f32 v6, v66, v67
	v_cvt_pk_bf16_f32 v7, v68, v69
	s_waitcnt lgkmcnt(13)
	v_mfma_f32_32x32x16_bf16 v[82:97], v[170:173], v[154:157], v[82:97]
	ds_read_b64_tr_b16 v[66:67], v190 offset:38912
	ds_read_b64_tr_b16 v[68:69], v190 offset:39424
	v_add_f32_e32 v2, v72, v2
	v_add_f32_e32 v2, v73, v2
	v_add_f32_e32 v2, v74, v2
	v_add_f32_e32 v2, v75, v2
	v_cvt_pk_bf16_f32 v8, v70, v71
	v_cvt_pk_bf16_f32 v9, v72, v73
	s_waitcnt lgkmcnt(14)
	v_mfma_f32_32x32x16_bf16 v[50:65], v[174:177], v[154:157], v[50:65]
	ds_read_b64_tr_b16 v[110:111], v190 offset:35840
	ds_read_b64_tr_b16 v[112:113], v190 offset:36352
	v_add_f32_e32 v2, v76, v2
	v_add_f32_e32 v2, v77, v2
	v_add_f32_e32 v2, v78, v2
	v_add_f32_e32 v127, v79, v2
	v_cvt_pk_bf16_f32 v2, v74, v75
	v_cvt_pk_bf16_f32 v3, v76, v77
	s_waitcnt lgkmcnt(14)
	v_mfma_f32_32x32x16_bf16 v[82:97], v[136:139], v[150:153], v[82:97]
	ds_read_b64_tr_b16 v[70:71], v190 offset:39936
	ds_read_b64_tr_b16 v[72:73], v190 offset:40448
	v_add_f32_e32 v4, v80, v127
	v_add_f32_e32 v4, v81, v4
	v_add_f32_e32 v74, 0, v4
	v_cvt_pk_bf16_f32 v4, v78, v79
	v_cvt_pk_bf16_f32 v5, v80, v81
	v_mfma_f32_32x32x16_bf16 v[50:65], v[122:125], v[150:153], v[50:65]
	s_nop 3
	v_exp_f32_e32 v82, v82
	v_exp_f32_e32 v83, v83
	v_exp_f32_e32 v84, v84
	v_exp_f32_e32 v85, v85
	s_nop 0
	v_exp_f32_e32 v86, v86
	v_exp_f32_e32 v87, v87
	v_exp_f32_e32 v88, v88
	v_exp_f32_e32 v89, v89
	s_nop 0
	v_exp_f32_e32 v90, v90
	v_exp_f32_e32 v91, v91
	v_exp_f32_e32 v92, v92
	v_exp_f32_e32 v93, v93
	s_nop 0
	v_exp_f32_e32 v94, v94
	v_exp_f32_e32 v95, v95
	v_exp_f32_e32 v96, v96
	v_exp_f32_e32 v97, v97
	v_exp_f32_e32 v50, v50
	v_exp_f32_e32 v51, v51
	v_exp_f32_e32 v52, v52
	v_exp_f32_e32 v53, v53
	s_nop 0
	v_exp_f32_e32 v54, v54
	v_exp_f32_e32 v55, v55
	v_exp_f32_e32 v56, v56
	v_exp_f32_e32 v57, v57
	s_nop 0
	v_exp_f32_e32 v58, v58
	v_exp_f32_e32 v59, v59
	v_exp_f32_e32 v60, v60
	v_exp_f32_e32 v61, v61
	s_nop 0
	v_exp_f32_e32 v62, v62
	v_exp_f32_e32 v63, v63
	v_exp_f32_e32 v64, v64
	v_exp_f32_e32 v65, v65
	s_waitcnt lgkmcnt(14)
	v_mfma_f32_32x32x16_bf16 v[18:33], v[146:149], v[114:117], v[18:33]
	v_add_f32_e32 v75, v82, v83
	v_add_f32_e32 v75, v84, v75
	v_add_f32_e32 v75, v85, v75
	v_add_f32_e32 v75, v86, v75
	v_add_f32_e32 v75, v87, v75
	v_add_f32_e32 v75, v88, v75
	v_add_f32_e32 v75, v89, v75
	s_waitcnt lgkmcnt(12)
	v_mfma_f32_32x32x16_bf16 v[34:49], v[146:149], v[98:101], v[34:49]
	v_add_f32_e32 v75, v90, v75
	v_add_f32_e32 v75, v91, v75
	v_add_f32_e32 v75, v92, v75
	v_add_f32_e32 v75, v93, v75
	v_add_f32_e32 v75, v94, v75
	v_add_f32_e32 v75, v95, v75
	v_add_f32_e32 v75, v96, v75
	s_waitcnt lgkmcnt(10)
	v_mfma_f32_32x32x16_bf16 v[18:33], v[10:13], v[118:121], v[18:33]
	v_add_f32_e32 v75, v97, v75
	v_add_f32_e32 v75, v50, v75
	v_add_f32_e32 v75, v51, v75
	v_add_f32_e32 v75, v52, v75
	v_add_f32_e32 v75, v53, v75
	v_add_f32_e32 v75, v54, v75
	v_add_f32_e32 v75, v55, v75
	s_waitcnt lgkmcnt(8)
	v_mfma_f32_32x32x16_bf16 v[34:49], v[10:13], v[102:105], v[34:49]
	v_add_f32_e32 v75, v56, v75
	v_add_f32_e32 v75, v57, v75
	v_add_f32_e32 v75, v58, v75
	v_add_f32_e32 v75, v59, v75
	v_add_f32_e32 v75, v60, v75
	v_add_f32_e32 v75, v61, v75
	v_add_f32_e32 v75, v62, v75
	s_waitcnt lgkmcnt(6)
	v_mfma_f32_32x32x16_bf16 v[18:33], v[6:9], v[106:109], v[18:33]
	v_add_f32_e32 v75, v63, v75
	v_add_f32_e32 v75, v64, v75
	v_add_f32_e32 v75, v65, v75
	v_add_f32_e32 v74, v126, v74
	v_add_f32_e32 v74, v74, v75
	v_cvt_pk_bf16_f32 v76, v82, v83
	v_cvt_pk_bf16_f32 v77, v84, v85
	s_waitcnt lgkmcnt(4)
	v_mfma_f32_32x32x16_bf16 v[34:49], v[6:9], v[66:69], v[34:49]
	v_cvt_pk_bf16_f32 v78, v86, v87
	v_cvt_pk_bf16_f32 v79, v88, v89
	v_cvt_pk_bf16_f32 v10, v90, v91
	v_cvt_pk_bf16_f32 v11, v92, v93
	v_cvt_pk_bf16_f32 v12, v94, v95
	v_cvt_pk_bf16_f32 v13, v96, v97
	v_cvt_pk_bf16_f32 v6, v50, v51
	s_waitcnt lgkmcnt(2)
; #define AT_SBAR() __builtin_amdgcn_sched_barrier(0)
; #define SBAR() __builtin_amdgcn_sched_barrier(0)
; #define RESC() do { if (resc) { asm volatile("s_waitcnt lgkmcnt(0)" ::: "memory"); \
;       _Pragma("unroll") for (int d_ = 0; d_ < 2; ++d_) _Pragma("unroll") for (int r = 0; r < 16; ++r) o[d_][r] *= wsf[crow(r, hi)]; } } while (0)
; #define PKW(P, B) cvtpk_s(P[B], P[B + 1])
; __device__ __forceinline__ void pv(f32x16* o, int vb, bf16x8 pa0, bf16x8 pa1, bf16x8 pa2, bf16x8 pa3) {
; #pragma unroll
;     for (int d0 = 0; d0 < 2; ++d0) { s16x4 lo[4], hi[4];
; #pragma unroll
;         for (int ks = 0; ks < 4; ++ks) {
;             asm volatile("ds_read_b64_tr_b16 %0,%1 offset:%c2" : "=&v"(lo[ks]) : "v"(vb), "i"(d0 * 4096 + ks * 1024) : "memory");
;             asm volatile("ds_read_b64_tr_b16 %0,%1 offset:%c2" : "=&v"(hi[ks]) : "v"(vb), "i"(d0 * 4096 + ks * 1024 + 512) : "memory"); }
;         asm volatile("s_waitcnt lgkmcnt(0)" ::: "memory"); AT_SBAR();
;     ...
;         o[d0] = __builtin_amdgcn_mfma_f32_32x32x16_bf16(pa0, AT_PK(0), o[d0], 0, 0, 0);
;         o[d0] = __builtin_amdgcn_mfma_f32_32x32x16_bf16(pa1, AT_PK(1), o[d0], 0, 0, 0);
;         o[d0] = __builtin_amdgcn_mfma_f32_32x32x16_bf16(pa2, AT_PK(2), o[d0], 0, 0, 0);
;         o[d0] = __builtin_amdgcn_mfma_f32_32x32x16_bf16(pa3, AT_PK(3), o[d0], 0, 0, 0);
;     ...
;     STEP(pB0, pB1, pA0, pA1, NT - 1, false, false, false); RESC();
;     { float sacc = pB0[0] + pB0[1]; _Pragma("unroll") for (int r = 2; r < 16; ++r) sacc += pB0[r]; _Pragma("unroll") for (int r = 0; r < 16; ++r) sacc += pB1[r]; l_reg += sacc;
;       pw0 = (u32x4){PKW(pB0, 0), PKW(pB0, 2), PKW(pB0, 4), PKW(pB0, 6)}; pw1 = (u32x4){PKW(pB0, 8), PKW(pB0, 10), PKW(pB0, 12), PKW(pB0, 14)}; pw2 = (u32x4){PKW(pB1, 0), PKW(pB1, 2), PKW(pB1, 4), PKW(pB1, 6)}; pw3 = (u32x4){PKW(pB1, 8), PKW(pB1, 10), PKW(pB1, 12), PKW(pB1, 14)};
;       SBAR(); const int vb0 = (int)(lds0 + LDS_V) + ((lane >> 4) & 1) * 32 + (lane & 3) * 8 + (4 * hi + ((lane & 15) >> 2)) * 64;
;       at::pv(o, vb0 + sl_cur, PAF(0), PAF(1), PAF(2), PAF(3)); }
	v_mfma_f32_32x32x16_bf16 v[18:33], v[2:5], v[110:113], v[18:33]
	v_cvt_pk_bf16_f32 v7, v52, v53
	v_cvt_pk_bf16_f32 v8, v54, v55
	v_cvt_pk_bf16_f32 v9, v56, v57
	v_cvt_pk_bf16_f32 v50, v58, v59
	v_cvt_pk_bf16_f32 v51, v60, v61
	v_cvt_pk_bf16_f32 v52, v62, v63
	v_cvt_pk_bf16_f32 v53, v64, v65
	s_waitcnt lgkmcnt(0)
	v_mfma_f32_32x32x16_bf16 v[34:49], v[2:5], v[70:73], v[34:49]
	v_add_u32_e32 v2, s16, v188
	v_add3_u32 v66, v2, v187, v189
	ds_read_b64_tr_b16 v[2:3],v66 offset:0
	ds_read_b64_tr_b16 v[4:5],v66 offset:512
	ds_read_b64_tr_b16 v[54:55],v66 offset:1024
	ds_read_b64_tr_b16 v[56:57],v66 offset:1536
	ds_read_b64_tr_b16 v[58:59],v66 offset:2048
	ds_read_b64_tr_b16 v[60:61],v66 offset:2560
	ds_read_b64_tr_b16 v[62:63],v66 offset:3072
	ds_read_b64_tr_b16 v[64:65],v66 offset:3584
	s_waitcnt lgkmcnt(0)
	s_nop 0
	v_mfma_f32_32x32x16_bf16 v[18:33], v[76:79], v[2:5], v[18:33]
	ds_read_b64_tr_b16 v[2:3],v66 offset:4096
	ds_read_b64_tr_b16 v[4:5],v66 offset:4608
	v_mfma_f32_32x32x16_bf16 v[18:33], v[10:13], v[54:57], v[18:33]
	ds_read_b64_tr_b16 v[54:55],v66 offset:5120
	ds_read_b64_tr_b16 v[56:57],v66 offset:5632
	v_mfma_f32_32x32x16_bf16 v[18:33], v[6:9], v[58:61], v[18:33]
	ds_read_b64_tr_b16 v[58:59],v66 offset:6144
	ds_read_b64_tr_b16 v[60:61],v66 offset:6656
	v_mfma_f32_32x32x16_bf16 v[18:33], v[50:53], v[62:65], v[18:33]
	ds_read_b64_tr_b16 v[62:63],v66 offset:7168
	ds_read_b64_tr_b16 v[64:65],v66 offset:7680
	s_waitcnt lgkmcnt(0)
	v_mfma_f32_32x32x16_bf16 v[34:49], v[76:79], v[2:5], v[34:49]
	v_mfma_f32_32x32x16_bf16 v[34:49], v[10:13], v[54:57], v[34:49]
	v_mfma_f32_32x32x16_bf16 v[34:49], v[6:9], v[58:61], v[34:49]
	v_mfma_f32_32x32x16_bf16 v[34:49], v[50:53], v[62:65], v[34:49]
	s_nop 15
	s_lshl_b32 s40, s48, 6
	s_add_u32 s42, s76, 0x10000
	s_addc_u32 s43, s77, 0
	s_add_u32 s42, s42, s40
	s_addc_u32 s43, s43, 0
	v_mov_b32_e32 v116, 0x20410
	v_mov_b32_e32 v120, 1
	s_and_saveexec_b64 s[44:45], s[62:63]
	s_cbranch_execz .Lgc_a1
	v_mov_b32_e32 v118, s42
	v_mov_b32_e32 v119, s43
	flat_atomic_add v117, v[118:119], v120 sc0
	s_waitcnt vmcnt(0) lgkmcnt(0)
	ds_write_b32 v116, v117
.Lgc_a1:
	s_or_b64 exec, exec, s[44:45]
	s_waitcnt lgkmcnt(0)
	s_barrier
	ds_read_b32 v117, v116
	s_waitcnt lgkmcnt(0)
	v_readfirstlane_b32 s41, v117
	s_mul_i32 s40, s48, 0x11000
	s_mul_i32 s46, s19, 0x2200
	s_add_u32 s40, s40, s46
	s_add_u32 s46, s76, 0xa200000
	s_addc_u32 s47, s77, 0
	s_add_u32 s46, s46, s40
	s_addc_u32 s47, s47, 0
	s_add_u32 s40, s46, 0x1000
	s_addc_u32 s45, s47, 0
	s_mov_b32 s44, s40
	v_lshlrev_b32_e32 v116, 4, v15
	v_lshlrev_b32_e32 v115, 2, v15
	v_add_u32_e32 v115, 0x1000, v115
	s_bitcmp1_b32 s41, 0
	s_cbranch_scc1 .Lgc_second
	global_store_dwordx4 v116, v[18:21], s[46:47] sc0 sc1
	global_store_dwordx4 v116, v[22:25], s[46:47] offset:1024 sc0 sc1
	global_store_dwordx4 v116, v[26:29], s[46:47] offset:2048 sc0 sc1
	global_store_dwordx4 v116, v[30:33], s[46:47] offset:3072 sc0 sc1
	global_store_dwordx4 v116, v[34:37], s[44:45] sc0 sc1
	global_store_dwordx4 v116, v[38:41], s[44:45] offset:1024 sc0 sc1
	global_store_dwordx4 v116, v[42:45], s[44:45] offset:2048 sc0 sc1
	global_store_dwordx4 v116, v[46:49], s[44:45] offset:3072 sc0 sc1
	global_store_dword v115, v74, s[44:45] sc0 sc1
	s_waitcnt vmcnt(0)
	s_barrier
	s_and_saveexec_b64 s[44:45], s[62:63]
	s_cbranch_execz .Lgc_f1
	v_mov_b32_e32 v118, s42
	v_mov_b32_e32 v119, s43
	flat_atomic_add v[118:119], v120 offset:32
.Lgc_f1:
	s_or_b64 exec, exec, s[44:45]
	v_readlane_b32 s36, v253, 25
	v_readlane_b32 s37, v253, 26
	v_readlane_b32 s38, v253, 27
	v_readlane_b32 s39, v253, 28
	v_readlane_b32 s40, v253, 29
	v_readlane_b32 s41, v253, 30
	v_readlane_b32 s42, v253, 31
	v_readlane_b32 s43, v253, 32
	v_readlane_b32 s44, v253, 33
	v_readlane_b32 s45, v253, 34
	v_readlane_b32 s46, v253, 35
	v_readlane_b32 s47, v253, 36
	v_readlane_b32 s48, v253, 37
	v_readlane_b32 s49, v253, 38
	v_readlane_b32 s50, v253, 39
	v_readlane_b32 s51, v253, 40
	s_branch .LBB0_439
.Lgc_second:
	s_add_i32 s41, s41, 1
	s_lshr_b32 s41, s41, 1
	s_mov_b64 s[36:37], exec
	s_and_b64 exec, exec, s[62:63]
	s_cbranch_execz .Lgc_w_done
	v_mov_b32_e32 v118, s42
	v_mov_b32_e32 v119, s43
	s_mov_b32 s40, 0x4000
.Lgc_spin:
	flat_load_dword v117, v[118:119] offset:32 sc1
	s_waitcnt vmcnt(0) lgkmcnt(0)
	v_readfirstlane_b32 s38, v117
	s_nop 3
	s_cmp_ge_u32 s38, s41
	s_cbranch_scc1 .Lgc_spun
	s_sleep 4
	s_sub_u32 s40, s40, 1
	s_cmp_lg_u32 s40, 0
	s_cbranch_scc1 .Lgc_spin
.Lgc_spun:
	buffer_inv sc1
	s_waitcnt vmcnt(0)
; __device__ __forceinline__ int crow(int r, int hi) { return (r & 3) + 8 * (r >> 2) + 4 * hi; }
; __device__ __forceinline__ unsigned cvtpk_s(float lo, float hi) { typedef __bf16 bf16x2_t __attribute__((ext_vector_type(2))); f32x2 v = {lo, hi}; bf16x2_t b = __builtin_convertvector(v, bf16x2_t); return __builtin_bit_cast(unsigned, b); }
; __device__ __forceinline__ void store_tile(const f32x16* o, const float* rli, bf16_t* stg, bf16_t* Ow, int pitch, float* ss, int lane, int r32, int hi) {
; #pragma unroll
;     for (int r = 0; r < 16; ++r) { const int orow = crow(r, hi);
; #pragma unroll
;         for (int d0 = 0; d0 < 2; ++d0) stg[orow * 64 + d0 * 32 + r32] = (bf16_t)(cvtpk_s(o[d0][r] * rli[r], 0.f) & 0xffffu); }
;     ...
;     { auto rr = __builtin_amdgcn_permlane32_swap(__float_as_uint(l_reg), __float_as_uint(l_reg), false, false); l_reg = __uint_as_float(rr[0]) + __uint_as_float(rr[1]); }
;     if (hi == 0) wsf[32 + r32] = l_reg; asm volatile("s_waitcnt lgkmcnt(0)" ::: "memory");
;     float rli[16];
; #pragma unroll
;     for (int r = 0; r < 16; ++r) rli[r] = __builtin_amdgcn_rcpf(wsf[32 + crow(r, hi)]);
;     at::store_tile(o, rli, (bf16_t*)(shm + LDS_OST) + wid * 2048, O + (long)(wid * QBLK) * OPITCH, OPITCH, ss + (long)(wid * QBLK) * 4, lane, r32, hi);
.Lgc_w_done:
	s_mov_b64 exec, s[36:37]
	s_barrier
	global_load_dwordx4 v[82:85], v116, s[46:47]
	global_load_dwordx4 v[86:89], v116, s[46:47] offset:1024
	global_load_dwordx4 v[90:93], v116, s[46:47] offset:2048
	global_load_dwordx4 v[94:97], v116, s[46:47] offset:3072
	global_load_dwordx4 v[98:101], v116, s[44:45]
	global_load_dwordx4 v[102:105], v116, s[44:45] offset:1024
	global_load_dwordx4 v[106:109], v116, s[44:45] offset:2048
	global_load_dwordx4 v[110:113], v116, s[44:45] offset:3072
	global_load_dword v114, v115, s[44:45]
	s_waitcnt vmcnt(0)
	v_pk_add_f32 v[18:19], v[18:19], v[82:83]
	v_pk_add_f32 v[20:21], v[20:21], v[84:85]
	v_pk_add_f32 v[22:23], v[22:23], v[86:87]
	v_pk_add_f32 v[24:25], v[24:25], v[88:89]
	v_pk_add_f32 v[26:27], v[26:27], v[90:91]
	v_pk_add_f32 v[28:29], v[28:29], v[92:93]
	v_pk_add_f32 v[30:31], v[30:31], v[94:95]
	v_pk_add_f32 v[32:33], v[32:33], v[96:97]
	v_pk_add_f32 v[34:35], v[34:35], v[98:99]
	v_pk_add_f32 v[36:37], v[36:37], v[100:101]
	v_pk_add_f32 v[38:39], v[38:39], v[102:103]
	v_pk_add_f32 v[40:41], v[40:41], v[104:105]
	v_pk_add_f32 v[42:43], v[42:43], v[106:107]
	v_pk_add_f32 v[44:45], v[44:45], v[108:109]
	v_pk_add_f32 v[46:47], v[46:47], v[110:111]
	v_pk_add_f32 v[48:49], v[48:49], v[112:113]
	v_add_f32_e32 v74, v74, v114
	v_mov_b32_e32 v2, v74
	s_nop 1
	v_permlane32_swap_b32_e32 v74, v2
	v_cmp_gt_u32_e32 vcc, 32, v15
	s_and_saveexec_b64 s[12:13], vcc
	v_add_f32_e32 v2, v74, v2
	v_lshl_add_u32 v3, v17, 2, s2
	ds_write_b32 v3, v2 offset:49280
	s_or_b64 exec, exec, s[12:13]
	s_waitcnt lgkmcnt(0)
	v_lshl_add_u32 v10, v186, 4, s2
	ds_read_b128 v[2:5], v10 offset:49280
	ds_read_b128 v[6:9], v10 offset:49312
	s_lshl_b64 s[12:13], s[4:5], 11
	s_add_u32 s10, s10, s12
	s_addc_u32 s11, s11, s13
	s_lshl_b64 s[4:5], s[4:5], 4
	s_add_u32 s8, s8, s4
	s_waitcnt lgkmcnt(1)
	v_rcp_f32_e32 v11, v2
	s_addc_u32 s2, s9, s5
	s_add_u32 s6, s10, s6
	s_addc_u32 s7, s11, s7
	s_lshl_b32 s4, s19, 12
	v_rcp_f32_e32 v12, v3
	v_rcp_f32_e32 v13, v4
	v_rcp_f32_e32 v50, v5
	s_waitcnt lgkmcnt(0)
	v_rcp_f32_e32 v51, v6
	ds_read_b128 v[2:5], v10 offset:49344
	v_rcp_f32_e32 v52, v7
	v_rcp_f32_e32 v53, v8
	v_rcp_f32_e32 v54, v9
	ds_read_b128 v[6:9], v10 offset:49376
	s_add_i32 s9, s4, 0
	v_mul_f32_e32 v10, v18, v11
	v_lshlrev_b32_e32 v0, 1, v0
	v_lshlrev_b32_e32 v17, 1, v17
	v_cvt_pk_bf16_f32 v10, v10, s0
	v_add3_u32 v0, s9, v0, v17
	ds_write_b16 v0, v10 offset:51200
	v_mul_f32_e32 v10, v34, v11
	v_cvt_pk_bf16_f32 v10, v10, s0
	ds_write_b16 v0, v10 offset:51264
	v_mul_f32_e32 v10, v19, v12
	v_cvt_pk_bf16_f32 v10, v10, s0
	ds_write_b16 v0, v10 offset:51328
	v_mul_f32_e32 v10, v35, v12
	v_cvt_pk_bf16_f32 v10, v10, s0
	ds_write_b16 v0, v10 offset:51392
	v_mul_f32_e32 v10, v20, v13
	v_cvt_pk_bf16_f32 v10, v10, s0
	ds_write_b16 v0, v10 offset:51456
	v_mul_f32_e32 v10, v36, v13
	v_cvt_pk_bf16_f32 v10, v10, s0
	ds_write_b16 v0, v10 offset:51520
	v_mul_f32_e32 v10, v21, v50
	v_cvt_pk_bf16_f32 v10, v10, s0
	ds_write_b16 v0, v10 offset:51584
	v_mul_f32_e32 v10, v37, v50
	v_cvt_pk_bf16_f32 v10, v10, s0
	ds_write_b16 v0, v10 offset:51648
	v_mul_f32_e32 v10, v22, v51
	v_cvt_pk_bf16_f32 v10, v10, s0
	ds_write_b16 v0, v10 offset:52224
	v_mul_f32_e32 v10, v38, v51
	v_cvt_pk_bf16_f32 v10, v10, s0
	ds_write_b16 v0, v10 offset:52288
	v_mul_f32_e32 v10, v23, v52
	v_cvt_pk_bf16_f32 v10, v10, s0
	ds_write_b16 v0, v10 offset:52352
	v_mul_f32_e32 v10, v39, v52
	v_cvt_pk_bf16_f32 v10, v10, s0
	ds_write_b16 v0, v10 offset:52416
	v_mul_f32_e32 v10, v24, v53
	v_cvt_pk_bf16_f32 v10, v10, s0
	ds_write_b16 v0, v10 offset:52480
	v_mul_f32_e32 v10, v40, v53
	v_cvt_pk_bf16_f32 v10, v10, s0
	s_waitcnt lgkmcnt(14)
	v_rcp_f32_e32 v2, v2
	ds_write_b16 v0, v10 offset:52544
	v_mul_f32_e32 v10, v25, v54
	v_cvt_pk_bf16_f32 v10, v10, s0
	v_rcp_f32_e32 v3, v3
	ds_write_b16 v0, v10 offset:52608
	v_mul_f32_e32 v10, v41, v54
	v_cvt_pk_bf16_f32 v10, v10, s0
	ds_write_b16 v0, v10 offset:52672
	v_mul_f32_e32 v10, v26, v2
	v_mul_f32_e32 v2, v42, v2
	v_cvt_pk_bf16_f32 v2, v2, s0
	v_rcp_f32_e32 v4, v4
	ds_write_b16 v0, v2 offset:53312
	v_mul_f32_e32 v2, v27, v3
	v_cvt_pk_bf16_f32 v2, v2, s0
	ds_write_b16 v0, v2 offset:53376
	v_mul_f32_e32 v2, v43, v3
	v_cvt_pk_bf16_f32 v2, v2, s0
	v_rcp_f32_e32 v5, v5
	ds_write_b16 v0, v2 offset:53440
	v_mul_f32_e32 v2, v28, v4
	v_cvt_pk_bf16_f32 v2, v2, s0
	ds_write_b16 v0, v2 offset:53504
	v_mul_f32_e32 v2, v44, v4
	v_cvt_pk_bf16_f32 v2, v2, s0
	s_waitcnt lgkmcnt(14)
; __device__ __forceinline__ int crow(int r, int hi) { return (r & 3) + 8 * (r >> 2) + 4 * hi; }
; __device__ __forceinline__ unsigned cvtpk_s(float lo, float hi) { typedef __bf16 bf16x2_t __attribute__((ext_vector_type(2))); f32x2 v = {lo, hi}; bf16x2_t b = __builtin_convertvector(v, bf16x2_t); return __builtin_bit_cast(unsigned, b); }
; __device__ __forceinline__ void store_tile(const f32x16* o, const float* rli, bf16_t* stg, bf16_t* Ow, int pitch, float* ss, int lane, int r32, int hi) {
; #pragma unroll
;     for (int r = 0; r < 16; ++r) { const int orow = crow(r, hi);
; #pragma unroll
;         for (int d0 = 0; d0 < 2; ++d0) stg[orow * 64 + d0 * 32 + r32] = (bf16_t)(cvtpk_s(o[d0][r] * rli[r], 0.f) & 0xffffu); }
;     asm volatile("s_waitcnt lgkmcnt(0)" ::: "memory");
; #pragma unroll
;     for (int i = 0; i < 4; ++i) { const int row = i * 8 + (lane >> 3), ch = lane & 7; const u32x4 v = *(const u32x4*)(stg + row * 64 + ch * 8);
;         { const bf16_t* gp_ = Ow + (long)row * pitch + ch * 8; asm volatile("global_store_dwordx4 %0, %1, off sc0 sc1\n\ts_nop 1" :: "v"(gp_), "v"(v) : "memory"); }
;         float s = 0.f;
; #pragma unroll
;         for (int j = 0; j < 4; ++j) { const float a = __uint_as_float(v[j] << 16), b = __uint_as_float(v[j] & 0xffff0000u); s += a * a + b * b; }
;         s += __shfl_xor(s, 1); s += __shfl_xor(s, 2); s += __shfl_xor(s, 4);
;         if (ch == 0) atomicAdd(ss + (long)row * 4, s); }
;     asm volatile("s_waitcnt lgkmcnt(0)" ::: "memory");
	v_rcp_f32_e32 v6, v6
	ds_write_b16 v0, v2 offset:53568
	v_mul_f32_e32 v2, v29, v5
	v_cvt_pk_bf16_f32 v2, v2, s0
	ds_write_b16 v0, v2 offset:53632
	v_mul_f32_e32 v2, v45, v5
	v_cvt_pk_bf16_f32 v2, v2, s0
	v_rcp_f32_e32 v7, v7
	ds_write_b16 v0, v2 offset:53696
	v_mul_f32_e32 v2, v30, v6
	v_cvt_pk_bf16_f32 v2, v2, s0
	ds_write_b16 v0, v2 offset:54272
	v_mul_f32_e32 v2, v46, v6
	v_cvt_pk_bf16_f32 v2, v2, s0
	v_rcp_f32_e32 v8, v8
	ds_write_b16 v0, v2 offset:54336
	v_mul_f32_e32 v2, v31, v7
	v_cvt_pk_bf16_f32 v2, v2, s0
	ds_write_b16 v0, v2 offset:54400
	v_mul_f32_e32 v2, v47, v7
	v_cvt_pk_bf16_f32 v2, v2, s0
	v_rcp_f32_e32 v9, v9
	ds_write_b16 v0, v2 offset:54464
	v_mul_f32_e32 v2, v32, v8
	v_cvt_pk_bf16_f32 v2, v2, s0
	ds_write_b16 v0, v2 offset:54528
	v_mul_f32_e32 v2, v48, v8
	v_cvt_pk_bf16_f32 v2, v2, s0
	ds_write_b16 v0, v2 offset:54592
	v_mul_f32_e32 v2, v33, v9
	v_cvt_pk_bf16_f32 v2, v2, s0
	ds_write_b16 v0, v2 offset:54656
	v_mul_f32_e32 v2, v49, v9
	v_cvt_pk_bf16_f32 v10, v10, s0
	v_cvt_pk_bf16_f32 v2, v2, s0
	v_and_b32_e32 v6, 7, v14
	ds_write_b16 v0, v10 offset:53248
	ds_write_b16 v0, v2 offset:54720
	v_lshlrev_b32_e32 v0, 4, v6
	v_lshrrev_b32_e32 v7, 3, v15
	v_add_u32_e32 v8, s9, v0
	s_waitcnt lgkmcnt(0)
	v_lshl_add_u32 v2, v7, 7, v8
	ds_read_b128 v[12:15], v2 offset:51200
	s_lshl_b64 s[4:5], s[0:1], 11
	s_add_u32 s6, s6, s4
	s_addc_u32 s7, s7, s5
	s_lshl_b64 s[0:1], s[0:1], 4
	s_waitcnt lgkmcnt(0)
	v_and_b32_e32 v3, 0xffff0000, v12
	v_lshlrev_b32_e32 v2, 16, v12
	v_mul_f32_e32 v3, v3, v3
	v_and_b32_e32 v4, 0xffff0000, v13
	v_fmac_f32_e32 v3, v2, v2
	v_lshlrev_b32_e32 v2, 16, v13
	v_mul_f32_e32 v4, v4, v4
	v_fmac_f32_e32 v4, v2, v2
	v_add_f32_e32 v2, v3, v4
	v_and_b32_e32 v4, 0xffff0000, v14
	v_lshlrev_b32_e32 v3, 16, v14
	v_mul_f32_e32 v4, v4, v4
	v_fmac_f32_e32 v4, v3, v3
	v_add_f32_e32 v2, v4, v2
	v_and_b32_e32 v4, 0xffff0000, v15
	v_lshlrev_b32_e32 v3, 16, v15
	v_mul_f32_e32 v4, v4, v4
	v_fmac_f32_e32 v4, v3, v3
	v_and_b32_e32 v3, 64, v220
	v_add_f32_e32 v5, v4, v2
	v_xor_b32_e32 v2, 1, v220
	v_add_u32_e32 v10, 64, v3
	v_cmp_lt_i32_e32 vcc, v2, v10
	s_add_u32 s0, s8, s0
	s_addc_u32 s1, s2, s1
	v_cndmask_b32_e32 v2, v220, v2, vcc
	v_lshlrev_b32_e32 v4, 2, v2
	ds_bpermute_b32 v9, v4, v5
	v_lshl_add_u64 v[2:3], s[6:7], 0, v[0:1]
	v_xor_b32_e32 v0, 2, v220
	v_cmp_lt_i32_e32 vcc, v0, v10
	s_add_u32 s4, s0, 0x200008
	s_waitcnt lgkmcnt(0)
	v_add_f32_e32 v9, v5, v9
	v_cndmask_b32_e32 v0, v220, v0, vcc
	v_lshlrev_b32_e32 v5, 2, v0
	s_addc_u32 s5, s1, 0
	ds_bpermute_b32 v11, v5, v9
	s_mov_b64 s[0:1], 0x12e40500
	v_lshl_add_u64 v[2:3], v[2:3], 0, s[0:1]
	v_lshlrev_b32_e32 v0, 11, v7
	v_lshl_add_u64 v[18:19], v[2:3], 0, v[0:1]
	v_xor_b32_e32 v0, 4, v220
	v_cmp_lt_i32_e64 s[0:1], v0, v10
	v_cmp_eq_u32_e32 vcc, 0, v6
	s_waitcnt lgkmcnt(0)
	v_add_f32_e32 v9, v9, v11
	v_cndmask_b32_e64 v0, v220, v0, s[0:1]
	v_lshlrev_b32_e32 v6, 2, v0
	ds_bpermute_b32 v10, v6, v9
	global_store_dwordx4 v[18:19], v[12:15], off sc0 sc1
	s_nop 1
	s_and_saveexec_b64 s[0:1], vcc
	v_readlane_b32 s36, v253, 25
	v_readlane_b32 s37, v253, 26
	v_readlane_b32 s38, v253, 27
	v_readlane_b32 s39, v253, 28
	v_readlane_b32 s40, v253, 29
	v_readlane_b32 s41, v253, 30
	v_readlane_b32 s42, v253, 31
	v_readlane_b32 s43, v253, 32
	v_readlane_b32 s44, v253, 33
	v_readlane_b32 s45, v253, 34
	v_readlane_b32 s46, v253, 35
	v_readlane_b32 s47, v253, 36
	v_readlane_b32 s48, v253, 37
	v_readlane_b32 s49, v253, 38
	v_readlane_b32 s50, v253, 39
	v_readlane_b32 s51, v253, 40
	s_cbranch_execz .LBB0_881
	v_lshlrev_b32_e32 v0, 4, v7
	v_lshl_add_u64 v[12:13], s[4:5], 0, v[0:1]
	s_waitcnt lgkmcnt(0)
	v_add_f32_e32 v0, v9, v10
	flat_atomic_add_f32 v[12:13], v0
